# MLA: softmax scale folded into q (phase 4); running-max offset fed as QK MFMA C operand, no-rescale path is one v_exp per score
# speedup vs baseline: 1.0181x; 1.0181x over previous
.LBB0_1709:
	s_andn2_b64 vcc, exec, s[0:1]
	s_cbranch_vccnz .LBB0_1638
	s_mul_hi_i32 s30, s29, 0x2aaaaaab
	s_lshr_b32 s0, s30, 31
	s_add_i32 s30, s30, s0
	s_mul_i32 s0, s30, -6
	s_add_i32 s12, s29, s0
	s_lshl_b32 s0, s30, 7
	s_ashr_i32 s1, s0, 31
	s_lshl_b64 s[6:7], s[0:1], 9
	s_add_u32 s6, s16, s6
	v_mov_b32_e32 v49, v186
	s_addc_u32 s7, s17, s7
	s_ashr_i32 s13, s12, 31
	s_lshl_b64 s[12:13], s[12:13], 16
	v_lshlrev_b32_e32 v16, 4, v49
	v_ashrrev_i32_e32 v50, 3, v49
	v_and_b32_e32 v48, 0x70, v16
	s_add_u32 s12, s24, s12
	v_lshl_or_b32 v132, v50, 9, v48
	s_addc_u32 s13, s25, s13
	v_add_u32_e32 v133, 0x4000, v132
	v_add_u32_e32 v134, 0x8000, v132
	v_add_u32_e32 v135, 0xc000, v132
	s_waitcnt vmcnt(63) expcnt(7) lgkmcnt(15)
	s_barrier
	global_load_dwordx4 v[16:19], v132, s[6:7]
	global_load_dwordx4 v[20:23], v133, s[6:7]
	global_load_dwordx4 v[24:27], v134, s[6:7]
	global_load_dwordx4 v[28:31], v135, s[6:7]
	global_load_dwordx4 v[32:35], v132, s[12:13]
	global_load_dwordx4 v[36:39], v133, s[12:13]
	global_load_dwordx4 v[40:43], v134, s[12:13]
	global_load_dwordx4 v[44:47], v135, s[12:13]
	v_mad_u64_u32 v[130:131], s[34:35], v50, s43, v[48:49]
	s_waitcnt vmcnt(7)
	ds_write_b128 v130, v[16:19]
	s_waitcnt vmcnt(6)
	ds_write_b128 v130, v[20:23] offset:4608
	s_waitcnt vmcnt(5)
	ds_write_b128 v130, v[24:27] offset:9216
	s_waitcnt vmcnt(4)
	ds_write_b128 v130, v[28:31] offset:13824
	s_waitcnt vmcnt(3)
	ds_write_b128 v130, v[32:35] offset:36864
	s_waitcnt vmcnt(2)
	ds_write_b128 v130, v[36:39] offset:41472
	s_waitcnt vmcnt(1)
	ds_write_b128 v130, v[40:43] offset:46080
	s_waitcnt vmcnt(0)
	ds_write_b128 v130, v[44:47] offset:50688
	global_load_dwordx4 v[96:99], v132, s[6:7] offset:128
	global_load_dwordx4 v[100:103], v133, s[6:7] offset:128
	global_load_dwordx4 v[104:107], v134, s[6:7] offset:128
	global_load_dwordx4 v[108:111], v135, s[6:7] offset:128
	v_lshrrev_b32_e32 v18, 1, v49
	v_and_b32_e32 v17, 0x5f, v49
	v_and_b32_e32 v16, 16, v18
	v_mad_u32_u24 v131, v17, s43, v16
	v_and_b32_e32 v17, 31, v49
	v_and_or_b32 v17, v18, s44, v17
	v_mad_u64_u32 v[128:129], s[34:35], v17, s43, v[16:17]
	global_load_dwordx4 v[64:67], v132, s[12:13] offset:128
	global_load_dwordx4 v[68:71], v133, s[12:13] offset:128
	global_load_dwordx4 v[72:75], v134, s[12:13] offset:128
	global_load_dwordx4 v[76:79], v135, s[12:13] offset:128
	s_waitcnt lgkmcnt(0)
	s_barrier
	ds_read_b128 v[16:19], v128
	ds_read_b128 v[84:87], v131 offset:41472
	ds_read_b128 v[80:83], v128 offset:4608
	ds_read_b128 v[136:139], v128 offset:32
	s_waitcnt lgkmcnt(2)
	v_mfma_f32_32x32x16_bf16 v[48:63], v[16:19], v[84:87], v[0:15]
	ds_read_b128 v[88:91], v131 offset:36864
	ds_read_b128 v[140:143], v128 offset:4640
	ds_read_b128 v[156:159], v131 offset:36896
	ds_read_b128 v[220:223], v131 offset:41504
	v_add_u32_e32 v129, 0xd800, v130
	s_waitcnt lgkmcnt(3)
	v_mfma_f32_32x32x16_bf16 v[32:47], v[16:19], v[88:91], v[0:15]
	v_mfma_f32_32x32x16_bf16 v[16:31], v[80:83], v[88:91], v[0:15]
	v_mfma_f32_32x32x16_bf16 v[0:15], v[80:83], v[84:87], v[0:15]
	s_waitcnt lgkmcnt(1)
	v_mfma_f32_32x32x16_bf16 v[32:47], v[136:139], v[156:159], v[32:47]
	s_waitcnt lgkmcnt(0)
	v_mfma_f32_32x32x16_bf16 v[48:63], v[136:139], v[220:223], v[48:63]
	v_mfma_f32_32x32x16_bf16 v[16:31], v[140:143], v[156:159], v[16:31]
	v_mfma_f32_32x32x16_bf16 v[0:15], v[140:143], v[220:223], v[0:15]
	ds_read_b128 v[224:227], v128 offset:64
	ds_read_b128 v[228:231], v128 offset:4672
	ds_read_b128 v[232:235], v131 offset:36928
	ds_read_b128 v[236:239], v131 offset:41536
	s_waitcnt lgkmcnt(1)
	v_mfma_f32_32x32x16_bf16 v[32:47], v[224:227], v[232:235], v[32:47]
	s_waitcnt lgkmcnt(0)
	v_mfma_f32_32x32x16_bf16 v[48:63], v[224:227], v[236:239], v[48:63]
	v_mfma_f32_32x32x16_bf16 v[16:31], v[228:231], v[232:235], v[16:31]
	v_mfma_f32_32x32x16_bf16 v[0:15], v[228:231], v[236:239], v[0:15]
	global_load_dwordx4 v[112:115], v132, s[6:7] offset:256
	global_load_dwordx4 v[116:119], v133, s[6:7] offset:256
	global_load_dwordx4 v[120:123], v134, s[6:7] offset:256
	global_load_dwordx4 v[124:127], v135, s[6:7] offset:256
	global_load_dwordx4 v[80:83], v132, s[12:13] offset:256
	global_load_dwordx4 v[84:87], v133, s[12:13] offset:256
	global_load_dwordx4 v[88:91], v134, s[12:13] offset:256
	global_load_dwordx4 v[92:95], v135, s[12:13] offset:256
	s_waitcnt vmcnt(15)
	ds_write_b128 v130, v[96:99] offset:18432
	s_waitcnt vmcnt(14)
	ds_write_b128 v130, v[100:103] offset:23040
	s_waitcnt vmcnt(13)
	ds_write_b128 v130, v[104:107] offset:27648
	s_waitcnt vmcnt(12)
	ds_write_b128 v130, v[108:111] offset:32256
	ds_read_b128 v[96:99], v128 offset:96
	ds_read_b128 v[100:103], v128 offset:4704
	ds_read_b128 v[104:107], v131 offset:36960
	ds_read_b128 v[108:111], v131 offset:41568
	s_waitcnt vmcnt(11)
	ds_write_b128 v130, v[64:67] offset:55296
	s_waitcnt vmcnt(10)
	ds_write_b128 v130, v[68:71] offset:59904
	s_waitcnt vmcnt(9)
	ds_write_b128 v130, v[72:75] offset:64512
	s_waitcnt vmcnt(8)
	ds_write_b128 v129, v[76:79] offset:13824
	s_waitcnt lgkmcnt(5)
	v_mfma_f32_32x32x16_bf16 v[32:47], v[96:99], v[104:107], v[32:47]
	s_waitcnt lgkmcnt(0)
	s_barrier
	v_mfma_f32_32x32x16_bf16 v[48:63], v[96:99], v[108:111], v[48:63]
	v_mfma_f32_32x32x16_bf16 v[16:31], v[100:103], v[104:107], v[16:31]
	v_mfma_f32_32x32x16_bf16 v[0:15], v[100:103], v[108:111], v[0:15]
	ds_read_b128 v[64:67], v128 offset:23040
	ds_read_b128 v[72:75], v128 offset:18432
	ds_read_b128 v[68:71], v131 offset:59904
	ds_read_b128 v[76:79], v131 offset:55296
	ds_read_b128 v[96:99], v128 offset:18464
	ds_read_b128 v[100:103], v128 offset:23072
	ds_read_b128 v[104:107], v131 offset:55328
	ds_read_b128 v[108:111], v131 offset:59936
	s_waitcnt lgkmcnt(4)
	v_mfma_f32_32x32x16_bf16 v[32:47], v[72:75], v[76:79], v[32:47]
	v_mfma_f32_32x32x16_bf16 v[48:63], v[72:75], v[68:71], v[48:63]
	v_mfma_f32_32x32x16_bf16 v[16:31], v[64:67], v[76:79], v[16:31]
	v_mfma_f32_32x32x16_bf16 v[0:15], v[64:67], v[68:71], v[0:15]
	global_load_dwordx4 v[136:139], v132, s[6:7] offset:384
	global_load_dwordx4 v[140:143], v133, s[6:7] offset:384
	global_load_dwordx4 v[156:159], v134, s[6:7] offset:384
	global_load_dwordx4 v[220:223], v135, s[6:7] offset:384
	global_load_dwordx4 v[64:67], v132, s[12:13] offset:384
	global_load_dwordx4 v[68:71], v133, s[12:13] offset:384
	global_load_dwordx4 v[72:75], v134, s[12:13] offset:384
	global_load_dwordx4 v[76:79], v135, s[12:13] offset:384
	ds_read_b128 v[224:227], v128 offset:23104
	ds_read_b128 v[132:135], v128 offset:18496
	ds_read_b128 v[228:231], v131 offset:55360
	ds_read_b128 v[232:235], v131 offset:59968
	s_waitcnt vmcnt(15)
	ds_write_b128 v130, v[112:115]
	s_waitcnt vmcnt(14)
	ds_write_b128 v130, v[116:119] offset:4608
	s_waitcnt vmcnt(13)
	ds_write_b128 v130, v[120:123] offset:9216
	s_waitcnt vmcnt(12)
	ds_write_b128 v130, v[124:127] offset:13824
	s_waitcnt lgkmcnt(9)
	v_mfma_f32_32x32x16_bf16 v[16:31], v[100:103], v[104:107], v[16:31]
	s_waitcnt lgkmcnt(8)
	v_mfma_f32_32x32x16_bf16 v[0:15], v[100:103], v[108:111], v[0:15]
	v_mfma_f32_32x32x16_bf16 v[32:47], v[96:99], v[104:107], v[32:47]
	v_mfma_f32_32x32x16_bf16 v[48:63], v[96:99], v[108:111], v[48:63]
	ds_read_b128 v[100:103], v128 offset:23136
	ds_read_b128 v[96:99], v128 offset:18528
	ds_read_b128 v[104:107], v131 offset:55392
	ds_read_b128 v[108:111], v131 offset:60000
	s_waitcnt vmcnt(11)
	ds_write_b128 v130, v[80:83] offset:36864
	s_waitcnt vmcnt(10)
	ds_write_b128 v130, v[84:87] offset:41472
	s_waitcnt vmcnt(9)
	ds_write_b128 v130, v[88:91] offset:46080
	s_waitcnt vmcnt(8)
	ds_write_b128 v130, v[92:95] offset:50688
	s_waitcnt lgkmcnt(13)
	v_mfma_f32_32x32x16_bf16 v[16:31], v[224:227], v[228:231], v[16:31]
	s_waitcnt lgkmcnt(0)
	s_barrier
	v_mfma_f32_32x32x16_bf16 v[0:15], v[224:227], v[232:235], v[0:15]
	v_mfma_f32_32x32x16_bf16 v[16:31], v[100:103], v[104:107], v[16:31]
	v_mfma_f32_32x32x16_bf16 v[0:15], v[100:103], v[108:111], v[0:15]
	ds_read_b128 v[100:103], v128 offset:32
	v_mfma_f32_32x32x16_bf16 v[32:47], v[132:135], v[228:231], v[32:47]
	v_mfma_f32_32x32x16_bf16 v[48:63], v[132:135], v[232:235], v[48:63]
	v_mfma_f32_32x32x16_bf16 v[32:47], v[96:99], v[104:107], v[32:47]
	ds_read_b128 v[104:107], v131 offset:36928
	v_mfma_f32_32x32x16_bf16 v[48:63], v[96:99], v[108:111], v[48:63]
	ds_read_b128 v[96:99], v128
	ds_read_b128 v[80:83], v128 offset:4608
	ds_read_b128 v[84:87], v131 offset:41472
	ds_read_b128 v[108:111], v131 offset:41536
	s_waitcnt lgkmcnt(1)
	v_mfma_f32_32x32x16_bf16 v[48:63], v[96:99], v[84:87], v[48:63]
	v_mfma_f32_32x32x16_bf16 v[0:15], v[80:83], v[84:87], v[0:15]
	ds_read_b128 v[84:87], v128 offset:4640
	ds_read_b128 v[88:91], v131 offset:36864
	s_waitcnt lgkmcnt(0)
	v_mfma_f32_32x32x16_bf16 v[16:31], v[80:83], v[88:91], v[16:31]
	ds_read_b128 v[80:83], v131 offset:41504
	ds_read_b128 v[92:95], v131 offset:36896
	s_waitcnt lgkmcnt(1)
	v_mfma_f32_32x32x16_bf16 v[48:63], v[100:103], v[80:83], v[48:63]
	s_waitcnt lgkmcnt(0)
	v_mfma_f32_32x32x16_bf16 v[16:31], v[84:87], v[92:95], v[16:31]
	v_mfma_f32_32x32x16_bf16 v[0:15], v[84:87], v[80:83], v[0:15]
	v_mfma_f32_32x32x16_bf16 v[32:47], v[96:99], v[88:91], v[32:47]
	ds_read_b128 v[88:91], v128 offset:64
	ds_read_b128 v[96:99], v128 offset:4672
	s_waitcnt vmcnt(7)
	ds_write_b128 v130, v[136:139] offset:18432
	s_waitcnt vmcnt(6)
	ds_write_b128 v130, v[140:143] offset:23040
	s_waitcnt vmcnt(5)
	ds_write_b128 v130, v[156:159] offset:27648
	s_waitcnt vmcnt(4)
	ds_write_b128 v130, v[220:223] offset:32256
	ds_read_b128 v[80:83], v128 offset:96
	v_mfma_f32_32x32x16_bf16 v[32:47], v[100:103], v[92:95], v[32:47]
	ds_read_b128 v[84:87], v128 offset:4704
	ds_read_b128 v[92:95], v131 offset:36960
	ds_read_b128 v[100:103], v131 offset:41568
	s_waitcnt vmcnt(3)
	ds_write_b128 v130, v[64:67] offset:55296
	s_waitcnt vmcnt(2)
	ds_write_b128 v130, v[68:71] offset:59904
	s_waitcnt vmcnt(1)
	ds_write_b128 v130, v[72:75] offset:64512
	s_waitcnt vmcnt(0)
	ds_write_b128 v129, v[76:79] offset:13824
	s_waitcnt lgkmcnt(13)
	v_mfma_f32_32x32x16_bf16 v[32:47], v[88:91], v[104:107], v[32:47]
	s_waitcnt lgkmcnt(0)
	s_barrier
	ds_read_b128 v[64:67], v128 offset:23040
	ds_read_b128 v[72:75], v128 offset:18432
	ds_read_b128 v[68:71], v131 offset:59904
	ds_read_b128 v[76:79], v128 offset:18464
	v_mfma_f32_32x32x16_bf16 v[48:63], v[88:91], v[108:111], v[48:63]
	ds_read_b128 v[88:91], v131 offset:55328
	v_mfma_f32_32x32x16_bf16 v[16:31], v[96:99], v[104:107], v[16:31]
	ds_read_b128 v[104:107], v131 offset:55392
	v_mfma_f32_32x32x16_bf16 v[0:15], v[96:99], v[108:111], v[0:15]
	ds_read_b128 v[96:99], v128 offset:18528
	ds_read_b128 v[108:111], v131 offset:60000
	v_mfma_f32_32x32x16_bf16 v[32:47], v[80:83], v[92:95], v[32:47]
	v_mfma_f32_32x32x16_bf16 v[48:63], v[80:83], v[100:103], v[48:63]
	ds_read_b128 v[80:83], v128 offset:23072
	v_mfma_f32_32x32x16_bf16 v[16:31], v[84:87], v[92:95], v[16:31]
	ds_read_b128 v[92:95], v131 offset:59936
	v_mfma_f32_32x32x16_bf16 v[0:15], v[84:87], v[100:103], v[0:15]
	ds_read_b128 v[84:87], v131 offset:55296
	ds_read_b128 v[100:103], v128 offset:23136
	s_waitcnt lgkmcnt(1)
	v_mfma_f32_32x32x16_bf16 v[32:47], v[72:75], v[84:87], v[32:47]
	v_mfma_f32_32x32x16_bf16 v[48:63], v[72:75], v[68:71], v[48:63]
	ds_read_b128 v[72:75], v131 offset:55360
	v_mfma_f32_32x32x16_bf16 v[16:31], v[64:67], v[84:87], v[16:31]
	ds_read_b128 v[84:87], v131 offset:59968
	v_mfma_f32_32x32x16_bf16 v[0:15], v[64:67], v[68:71], v[0:15]
	ds_read_b128 v[64:67], v128 offset:18496
	ds_read_b128 v[68:71], v128 offset:23104
	s_waitcnt lgkmcnt(0)
	s_barrier
	v_mfma_f32_32x32x16_bf16 v[32:47], v[76:79], v[88:91], v[32:47]
	v_mfma_f32_32x32x16_bf16 v[48:63], v[76:79], v[92:95], v[48:63]
	v_mfma_f32_32x32x16_bf16 v[16:31], v[80:83], v[88:91], v[16:31]
	v_mfma_f32_32x32x16_bf16 v[0:15], v[80:83], v[92:95], v[0:15]
	v_mfma_f32_32x32x16_bf16 v[32:47], v[64:67], v[72:75], v[32:47]
	v_mfma_f32_32x32x16_bf16 v[48:63], v[64:67], v[84:87], v[48:63]
	v_mad_u64_u32 v[64:65], s[6:7], s30, -12, v[154:155]
	s_mulk_i32 s30, 0xffe8
	v_cmp_lt_i32_e32 vcc, 7, v64
	v_add_u32_e32 v160, s30, v218
	v_mfma_f32_32x32x16_bf16 v[16:31], v[68:71], v[72:75], v[16:31]
	v_mfma_f32_32x32x16_bf16 v[0:15], v[68:71], v[84:87], v[0:15]
	v_add_u32_e32 v68, s0, v163
	v_or_b32_e32 v66, v68, v164
	v_ashrrev_i32_e32 v67, 31, v66
	v_mfma_f32_32x32x16_bf16 v[32:47], v[96:99], v[104:107], v[32:47]
	v_mfma_f32_32x32x16_bf16 v[48:63], v[96:99], v[108:111], v[48:63]
	v_mfma_f32_32x32x16_bf16 v[16:31], v[100:103], v[104:107], v[16:31]
	v_mfma_f32_32x32x16_bf16 v[0:15], v[100:103], v[108:111], v[0:15]
	s_nop 7
	s_nop 7
	v_mul_f32_e32 v32, 0x3e16c740, v32
	v_mul_f32_e32 v33, 0x3e16c740, v33
	v_mul_f32_e32 v34, 0x3e16c740, v34
	v_mul_f32_e32 v35, 0x3e16c740, v35
	v_mul_f32_e32 v36, 0x3e16c740, v36
	v_mul_f32_e32 v37, 0x3e16c740, v37
	v_mul_f32_e32 v38, 0x3e16c740, v38
	v_mul_f32_e32 v39, 0x3e16c740, v39
	v_mul_f32_e32 v40, 0x3e16c740, v40
	v_mul_f32_e32 v41, 0x3e16c740, v41
	v_mul_f32_e32 v42, 0x3e16c740, v42
	v_mul_f32_e32 v43, 0x3e16c740, v43
	v_mul_f32_e32 v44, 0x3e16c740, v44
	v_mul_f32_e32 v45, 0x3e16c740, v45
	v_mul_f32_e32 v46, 0x3e16c740, v46
	v_mul_f32_e32 v47, 0x3e16c740, v47
	v_mul_f32_e32 v48, 0x3e16c740, v48
	v_mul_f32_e32 v49, 0x3e16c740, v49
	v_mul_f32_e32 v50, 0x3e16c740, v50
	v_mul_f32_e32 v51, 0x3e16c740, v51
	v_mul_f32_e32 v52, 0x3e16c740, v52
	v_mul_f32_e32 v53, 0x3e16c740, v53
	v_mul_f32_e32 v54, 0x3e16c740, v54
	v_mul_f32_e32 v55, 0x3e16c740, v55
	v_mul_f32_e32 v56, 0x3e16c740, v56
	v_mul_f32_e32 v57, 0x3e16c740, v57
	v_mul_f32_e32 v58, 0x3e16c740, v58
	v_mul_f32_e32 v59, 0x3e16c740, v59
	v_mul_f32_e32 v60, 0x3e16c740, v60
	v_mul_f32_e32 v61, 0x3e16c740, v61
	v_mul_f32_e32 v62, 0x3e16c740, v62
	v_mul_f32_e32 v63, 0x3e16c740, v63
	v_mul_f32_e32 v16, 0x3e16c740, v16
	v_mul_f32_e32 v17, 0x3e16c740, v17
	v_mul_f32_e32 v18, 0x3e16c740, v18
	v_mul_f32_e32 v19, 0x3e16c740, v19
	v_mul_f32_e32 v20, 0x3e16c740, v20
	v_mul_f32_e32 v21, 0x3e16c740, v21
	v_mul_f32_e32 v22, 0x3e16c740, v22
	v_mul_f32_e32 v23, 0x3e16c740, v23
	v_mul_f32_e32 v24, 0x3e16c740, v24
	v_mul_f32_e32 v25, 0x3e16c740, v25
	v_mul_f32_e32 v26, 0x3e16c740, v26
	v_mul_f32_e32 v27, 0x3e16c740, v27
	v_mul_f32_e32 v28, 0x3e16c740, v28
	v_mul_f32_e32 v29, 0x3e16c740, v29
	v_mul_f32_e32 v30, 0x3e16c740, v30
	v_mul_f32_e32 v31, 0x3e16c740, v31
	v_mul_f32_e32 v0, 0x3e16c740, v0
	v_mul_f32_e32 v1, 0x3e16c740, v1
	v_mul_f32_e32 v2, 0x3e16c740, v2
	v_mul_f32_e32 v3, 0x3e16c740, v3
	v_mul_f32_e32 v4, 0x3e16c740, v4
	v_mul_f32_e32 v5, 0x3e16c740, v5
	v_mul_f32_e32 v6, 0x3e16c740, v6
	v_mul_f32_e32 v7, 0x3e16c740, v7
	v_mul_f32_e32 v8, 0x3e16c740, v8
	v_mul_f32_e32 v9, 0x3e16c740, v9
	v_mul_f32_e32 v10, 0x3e16c740, v10
	v_mul_f32_e32 v11, 0x3e16c740, v11
	v_mul_f32_e32 v12, 0x3e16c740, v12
	v_mul_f32_e32 v13, 0x3e16c740, v13
	v_mul_f32_e32 v14, 0x3e16c740, v14
	v_mul_f32_e32 v15, 0x3e16c740, v15
	s_and_saveexec_b64 s[0:1], vcc
	s_xor_b64 s[6:7], exec, s[0:1]
	s_cbranch_execz .LBB0_1712
	v_lshl_or_b32 v70, v66, 4, v165
	v_ashrrev_i32_e32 v71, 31, v70
	v_lshlrev_b64 v[70:71], 2, v[70:71]
	v_lshl_add_u64 v[72:73], s[14:15], 0, v[70:71]
	global_load_dword v65, v[72:73], off
	v_lshl_add_u64 v[70:71], s[10:11], 0, v[70:71]
	global_load_dword v69, v[70:71], off
	v_and_b32_e32 v71, 64, v194
	v_xor_b32_e32 v70, 16, v194
	v_add_u32_e32 v71, 64, v71
	v_cmp_lt_i32_e64 s[0:1], v70, v71
	v_lshl_add_u64 v[66:67], v[66:67], 3, v[160:161]
	s_nop 0
	v_cndmask_b32_e64 v70, v194, v70, s[0:1]
	v_lshlrev_b32_e32 v70, 2, v70
	ds_bpermute_b32 v72, v70, v32
	ds_bpermute_b32 v73, v70, v48
	v_mad_u64_u32 v[70:71], s[0:1], v66, s38, v[152:153]
	v_mad_i32_i24 v71, v67, s38, v71
	s_waitcnt vmcnt(1) lgkmcnt(1)
	v_mul_f32_e32 v66, v65, v72
	s_waitcnt lgkmcnt(0)
	v_mul_f32_e32 v65, v65, v73
	v_cndmask_b32_e64 v66, v66, -v66, s[4:5]
	v_cndmask_b32_e64 v65, v65, -v65, s[4:5]
	s_waitcnt vmcnt(0)
	v_fmac_f32_e32 v66, v69, v32
	v_fmac_f32_e32 v65, v69, v48
	v_cvt_pk_bf16_f32 v66, v66, s0
	v_cvt_pk_bf16_f32 v65, v65, s0
	global_store_short v[70:71], v66, off offset:128
	global_store_short v[70:71], v65, off offset:320

.LBB0_1934:
	s_and_b32 s0, s80, 15
	s_mul_i32 s0, s0, 0x180000
	v_readlane_b32 s1, v255, 10
	s_add_u32 s0, s1, s0
	v_readlane_b32 s1, v255, 11
	s_addc_u32 s1, s1, 0
	s_ashr_i32 s2, s41, 4
	s_add_i32 s3, s41, 0xfffffe00
	s_sub_i32 s2, 63, s2
	s_lshr_b32 s3, s3, 4
	v_mov_b32_e32 v0, v186
	s_cmpk_lt_i32 s41, 0x200
	s_cselect_b32 s3, s2, s3
	v_ashrrev_i32_e32 v1, 1, v0
	v_and_b32_e32 v1, 0xffffffe0, v1
	v_lshl_add_u32 v139, s3, 7, v1
	s_waitcnt vmcnt(0)
	v_and_or_b32 v8, v0, 15, v139
	s_lshl_b32 s2, s41, 10
	v_or_b32_e32 v132, 16, v8
	s_and_b32 s4, s2, 0x2000
	s_mov_b32 s5, s77
	v_ashrrev_i32_e32 v133, 31, v132
	v_bfe_u32 v138, v0, 4, 2
	v_readlane_b32 s6, v254, 58
	v_ashrrev_i32_e32 v9, 31, v8
	v_lshl_add_u64 v[128:129], v[132:133], 0, s[4:5]
	s_and_b32 s12, s41, 7
	v_lshlrev_b32_e32 v160, 4, v138
	v_readlane_b32 s7, v254, 59
	v_lshl_add_u64 v[130:131], v[8:9], 0, s[4:5]
	v_lshlrev_b64 v[8:9], 3, v[128:129]
	v_lshl_add_u64 v[10:11], s[6:7], 0, v[160:161]
	v_lshlrev_b64 v[0:1], 3, v[130:131]
	s_movk_i32 s2, 0xc0
	v_or_b32_e32 v8, s12, v8
	v_or_b32_e32 v0, s12, v0
	v_mad_u64_u32 v[20:21], s[4:5], v8, s2, v[10:11]
	v_mad_u64_u32 v[16:17], s[6:7], v0, s2, v[10:11]
	s_and_b32 s4, s41, 15
	v_mad_i32_i24 v17, v1, s2, v17
	v_mad_i32_i24 v21, v9, s2, v21
	v_mov_b32_e32 v136, 0xee013f39
	v_mov_b32_e32 v172, v136
	v_mov_b32_e32 v173, v136
	v_mov_b32_e32 v164, 0
	v_mov_b32_e32 v165, 0
	v_mov_b32_e32 v166, 0
	v_mov_b32_e32 v167, 0
	v_mov_b32_e32 v168, 0
	v_mov_b32_e32 v169, 0
	v_mov_b32_e32 v170, 0
	v_mov_b32_e32 v171, 0
	v_mov_b32_e32 v48, v161
	v_mov_b32_e32 v76, v161
	v_mov_b32_e32 v84, v161
	v_mov_b32_e32 v92, v161
	v_mov_b32_e32 v40, v161
	v_mov_b32_e32 v72, v161
	v_mov_b32_e32 v80, v161
	v_mov_b32_e32 v88, v161
	s_mul_i32 s5, s4, 0x180000
	v_readlane_b32 s6, v254, 62
	v_mov_b32_e32 v32, v186
	global_load_dwordx4 v[0:3], v[16:17], off offset:64
	global_load_dwordx4 v[4:7], v[16:17], off offset:128
	global_load_dwordx4 v[8:11], v[20:21], off
	global_load_dwordx4 v[12:15], v[20:21], off offset:64
	s_nop 0
	global_load_dwordx4 v[16:19], v[16:17], off
	s_nop 0
	global_load_dwordx4 v[20:23], v[20:21], off offset:128
	s_add_u32 s6, s6, s5
	v_readlane_b32 s5, v254, 63
	s_addc_u32 s7, s5, 0
	v_add_u32_e32 v42, 0x100, v32
	s_lshl_b32 s4, s4, 20
	v_readlane_b32 s5, v254, 60
	v_ashrrev_i32_e32 v33, 31, v32
	v_ashrrev_i32_e32 v43, 31, v42
	s_add_u32 s4, s5, s4
	v_readlane_b32 s5, v254, 61
	v_lshl_add_u64 v[34:35], v[32:33], 4, s[6:7]
	v_lshl_add_u64 v[24:25], v[42:43], 4, s[6:7]
	v_lshlrev_b32_e32 v33, 4, v32
	v_ashrrev_i32_e32 v32, 3, v32
	v_ashrrev_i32_e32 v42, 3, v42
	s_addc_u32 s5, s5, 0
	s_lshl_b32 s13, s3, 1
	s_movk_i32 s3, 0x2000
	v_and_b32_e32 v160, 0x70, v33
	v_ashrrev_i32_e32 v33, 31, v32
	v_ashrrev_i32_e32 v43, 31, v42
	global_load_dwordx4 v[28:31], v[34:35], off
	s_nop 0
	global_load_dwordx4 v[24:27], v[24:25], off
	v_add_co_u32_e32 v34, vcc, s3, v34
	v_lshl_add_u64 v[44:45], s[4:5], 0, v[160:161]
	v_lshlrev_b64 v[32:33], 14, v[32:33]
	v_lshlrev_b64 v[42:43], 14, v[42:43]
	v_addc_co_u32_e32 v35, vcc, 0, v35, vcc
	v_lshl_add_u64 v[36:37], v[44:45], 0, v[32:33]
	v_lshl_add_u64 v[42:43], v[44:45], 0, v[42:43]
	global_load_dwordx4 v[32:35], v[34:35], off
	s_nop 0
	global_load_dwordx4 v[36:39], v[36:37], off
	s_add_u32 s6, s6, 0x3000
	global_load_dwordx4 v[44:47], v[42:43], off
	v_mov_b32_e32 v42, v186
	s_addc_u32 s7, s7, 0
	s_movk_i32 s15, 0x2000
	v_ashrrev_i32_e32 v43, 31, v42
	v_add_u32_e32 v68, 0x100, v42
	v_lshl_add_u64 v[50:51], v[42:43], 4, s[6:7]
	v_ashrrev_i32_e32 v69, 31, v68
	v_lshlrev_b32_e32 v41, 4, v42
	v_ashrrev_i32_e32 v42, 3, v42
	v_lshl_add_u64 v[56:57], v[68:69], 4, s[6:7]
	v_and_b32_e32 v160, 0x70, v41
	v_ashrrev_i32_e32 v43, 31, v42
	global_load_dwordx4 v[52:55], v[50:51], off
	s_nop 0
	global_load_dwordx4 v[56:59], v[56:57], off
	v_add_co_u32_e32 v50, vcc, s3, v50
	v_lshl_add_u64 v[70:71], s[4:5], 0, v[160:161]
	v_lshlrev_b64 v[42:43], 14, v[42:43]
	v_addc_co_u32_e32 v51, vcc, 0, v51, vcc
	v_lshl_add_u64 v[42:43], v[70:71], 0, v[42:43]
	global_load_dwordx4 v[60:63], v[50:51], off
	global_load_dwordx4 v[64:67], v[42:43], off offset:128
	v_ashrrev_i32_e32 v42, 3, v68
	v_ashrrev_i32_e32 v43, 31, v42
	v_lshlrev_b64 v[42:43], 14, v[42:43]
	v_lshl_add_u64 v[42:43], v[70:71], 0, v[42:43]
	global_load_dwordx4 v[68:71], v[42:43], off offset:128
	v_mov_b32_e32 v160, v161
	s_mov_b32 s14, 0
	v_mov_b32_e32 v49, v48
	v_mov_b32_e32 v50, v48
	v_mov_b32_e32 v51, v48
	v_mov_b32_e32 v77, v76
	v_mov_b32_e32 v78, v76
	v_mov_b32_e32 v79, v76
	v_mov_b32_e32 v85, v84
	v_mov_b32_e32 v86, v84
	v_mov_b32_e32 v87, v84
	v_mov_b32_e32 v93, v92
	v_mov_b32_e32 v94, v92
	v_mov_b32_e32 v95, v92
	v_mov_b32_e32 v41, v40
	v_mov_b32_e32 v42, v40
	v_mov_b32_e32 v43, v40
	v_mov_b32_e32 v73, v72
	v_mov_b32_e32 v74, v72
	v_mov_b32_e32 v75, v72
	v_mov_b32_e32 v81, v80
	v_mov_b32_e32 v82, v80
	v_mov_b32_e32 v83, v80
	v_mov_b32_e32 v89, v88
	v_mov_b32_e32 v90, v88
	v_mov_b32_e32 v91, v88
	v_mov_b32_e32 v137, v136
	v_or_b32_e32 v133, 31, v139
	v_mov_b64_e32 v[134:135], v[160:161]
	s_branch .LBB0_1939
.LBB0_1935:
	v_mov_b32_e32 v103, v101
	s_nop 1
	v_permlane16_swap_b32_e32 v101, v103
	v_max_f32_e32 v101, v103, v101
	v_mov_b32_e32 v103, v101
	s_nop 1
	v_permlane32_swap_b32_e32 v101, v103
	v_max3_f32 v101, v137, v101, v103
	v_sub_f32_e32 v103, v137, v101
	v_mul_f32_e32 v103, 1.0, v103
	v_exp_f32_e32 v108, v103
	v_mov_b32_e32 v137, v101
	v_mul_f32_e32 v135, v135, v108
	v_pk_mul_f32 v[42:43], v[42:43], v[108:109] op_sel_hi:[1,0]
	v_pk_mul_f32 v[40:41], v[40:41], v[108:109] op_sel_hi:[1,0]
	v_pk_mul_f32 v[74:75], v[74:75], v[108:109] op_sel_hi:[1,0]
	v_pk_mul_f32 v[72:73], v[72:73], v[108:109] op_sel_hi:[1,0]
	v_pk_mul_f32 v[82:83], v[82:83], v[108:109] op_sel_hi:[1,0]
	v_pk_mul_f32 v[80:81], v[80:81], v[108:109] op_sel_hi:[1,0]
	v_pk_mul_f32 v[90:91], v[90:91], v[108:109] op_sel_hi:[1,0]
	v_pk_mul_f32 v[88:89], v[88:89], v[108:109] op_sel_hi:[1,0]
	v_mul_f32_e32 v108, -1.0, v101
	v_fmamk_f32 v101, v149, 0x3f800000, v108
	v_exp_f32_e32 v101, v101
	v_fmamk_f32 v103, v148, 0x3f800000, v108
	v_exp_f32_e32 v103, v103
	v_fmamk_f32 v105, v147, 0x3f800000, v108
	v_exp_f32_e32 v105, v105
	v_fmamk_f32 v107, v146, 0x3f800000, v108
	v_exp_f32_e32 v107, v107
	v_add_f32_e32 v109, v103, v101
	v_add_f32_e32 v109, v105, v109
	v_add_f32_e32 v146, v107, v109
	v_fmamk_f32 v109, v145, 0x3f800000, v108
	v_exp_f32_e32 v109, v109
	v_fmamk_f32 v110, v144, 0x3f800000, v108
	v_exp_f32_e32 v110, v110
	v_fmamk_f32 v111, v143, 0x3f800000, v108
	v_exp_f32_e32 v111, v111
	v_fmamk_f32 v142, v142, 0x3f800000, v108
	v_exp_f32_e32 v142, v142
	v_fmamk_f32 v97, v97, 0x3f800000, v108
	v_add_f32_e32 v143, v109, v146
	v_exp_f32_e32 v97, v97
	v_fmamk_f32 v98, v98, 0x3f800000, v108
	v_add_f32_e32 v143, v110, v143
	v_exp_f32_e32 v98, v98
	v_fmamk_f32 v99, v99, 0x3f800000, v108
	v_add_f32_e32 v143, v111, v143
	v_exp_f32_e32 v99, v99
	v_fmamk_f32 v100, v100, 0x3f800000, v108
	v_add_f32_e32 v143, v142, v143
	v_exp_f32_e32 v100, v100
	v_fmamk_f32 v102, v102, 0x3f800000, v108
	v_add_f32_e32 v143, v97, v143
	v_exp_f32_e32 v102, v102
	v_fmamk_f32 v104, v104, 0x3f800000, v108
	v_fmamk_f32 v106, v106, 0x3f800000, v108
	v_fmac_f32_e32 v108, 1.0, v96
	v_add_f32_e32 v143, v98, v143
	v_exp_f32_e32 v104, v104
	v_exp_f32_e32 v106, v106
	v_exp_f32_e32 v108, v108
	v_add_f32_e32 v143, v99, v143
	v_add_f32_e32 v143, v100, v143
	v_add_f32_e32 v96, v102, v143

.LBB0_1941:
	s_add_i32 s3, s2, 0xffffff40
	v_cmp_le_i32_e32 vcc, s3, v133
	s_and_saveexec_b64 s[8:9], vcc
	s_cbranch_execz .LBB0_1959
	s_add_i32 s3, s2, 0xffffff7f
	v_cmp_le_i32_e32 vcc, s3, v139
	s_and_saveexec_b64 s[10:11], vcc
	s_xor_b64 s[10:11], exec, s[10:11]
	s_cbranch_execz .LBB0_1950
	ds_read_b128 v[96:99], v244
	ds_read_b128 v[104:107], v244 offset:64
	ds_read_b128 v[108:111], v244 offset:3392
	ds_read_b128 v[116:119], v244 offset:6720
	ds_read_b128 v[124:127], v244 offset:6784
	ds_read_b128 v[142:145], v244 offset:10048
	s_waitcnt lgkmcnt(5)
	v_mfma_f32_16x16x32_bf16 v[100:103], v[96:99], v[16:19], v[164:167]
	v_mfma_f32_16x16x32_bf16 v[96:99], v[96:99], v[8:11], v[168:171]
	s_waitcnt lgkmcnt(4)
	v_mfma_f32_16x16x32_bf16 v[100:103], v[104:107], v[0:3], v[100:103]
	v_mfma_f32_16x16x32_bf16 v[96:99], v[104:107], v[12:15], v[96:99]
	ds_read_b128 v[104:107], v244 offset:128
	s_waitcnt lgkmcnt(0)
	v_mfma_f32_16x16x32_bf16 v[112:115], v[104:107], v[4:7], v[100:103]
	s_nop 3
	ds_read_b128 v[100:103], v244 offset:3328
	v_mfma_f32_16x16x32_bf16 v[96:99], v[104:107], v[20:23], v[96:99]
	s_waitcnt lgkmcnt(0)
	v_mfma_f32_16x16x32_bf16 v[104:107], v[100:103], v[16:19], v[164:167]
	v_mfma_f32_16x16x32_bf16 v[100:103], v[100:103], v[8:11], v[168:171]
	v_mfma_f32_16x16x32_bf16 v[104:107], v[108:111], v[0:3], v[104:107]
	v_mfma_f32_16x16x32_bf16 v[100:103], v[108:111], v[12:15], v[100:103]
	ds_read_b128 v[108:111], v244 offset:3456
	s_waitcnt lgkmcnt(0)
	v_mfma_f32_16x16x32_bf16 v[120:123], v[108:111], v[4:7], v[104:107]
	v_mfma_f32_16x16x32_bf16 v[104:107], v[108:111], v[20:23], v[100:103]
	s_nop 3
	ds_read_b128 v[100:103], v244 offset:6656
	s_waitcnt lgkmcnt(0)
	v_mfma_f32_16x16x32_bf16 v[108:111], v[100:103], v[16:19], v[164:167]
	v_mfma_f32_16x16x32_bf16 v[100:103], v[100:103], v[8:11], v[168:171]
	v_mfma_f32_16x16x32_bf16 v[108:111], v[116:119], v[0:3], v[108:111]
	v_mfma_f32_16x16x32_bf16 v[100:103], v[116:119], v[12:15], v[100:103]
	v_mfma_f32_16x16x32_bf16 v[116:119], v[124:127], v[4:7], v[108:111]
	s_nop 5
	ds_read_b128 v[108:111], v244 offset:9984
	v_mfma_f32_16x16x32_bf16 v[100:103], v[124:127], v[20:23], v[100:103]
	s_waitcnt lgkmcnt(0)
	v_mfma_f32_16x16x32_bf16 v[124:127], v[108:111], v[16:19], v[164:167]
	v_mfma_f32_16x16x32_bf16 v[108:111], v[108:111], v[8:11], v[168:171]
	v_mfma_f32_16x16x32_bf16 v[124:127], v[142:145], v[0:3], v[124:127]
	v_mfma_f32_16x16x32_bf16 v[108:111], v[142:145], v[12:15], v[108:111]
	ds_read_b128 v[142:145], v244 offset:10112
	s_waitcnt lgkmcnt(0)
	v_mfma_f32_16x16x32_bf16 v[124:127], v[142:145], v[4:7], v[124:127]
	v_mfma_f32_16x16x32_bf16 v[108:111], v[142:145], v[20:23], v[108:111]
	v_max_f32_e32 v142, v113, v112
	v_max3_f32 v142, v142, v114, v115
	v_max3_f32 v142, v142, v120, v121
	v_max3_f32 v142, v142, v122, v123
	v_max3_f32 v142, v142, v116, v117
	v_max3_f32 v142, v142, v118, v119
	s_nop 0
	v_max3_f32 v142, v142, v124, v125
	v_max3_f32 v142, v142, v126, v127
	v_sub_f32_e32 v143, v142, v172

	v_cmp_lt_f32_e32 vcc, s42, v143
	s_cbranch_vccz .LBB0_1945
	v_mov_b32_e32 v143, v142
	s_nop 1
	v_permlane16_swap_b32_e32 v142, v143
	v_max_f32_e32 v142, v143, v142
	v_mov_b32_e32 v143, v142
	s_nop 1
	v_permlane32_swap_b32_e32 v142, v143
	v_max3_f32 v146, v172, v142, v143
	v_sub_f32_e32 v136, v172, v146

	v_exp_f32_e32 v136, v136
	v_mov_b32_e32 v147, v137
	v_mul_f32_e32 v134, v134, v136
	v_pk_mul_f32 v[50:51], v[50:51], v[136:137] op_sel_hi:[1,0]
	v_pk_mul_f32 v[48:49], v[48:49], v[136:137] op_sel_hi:[1,0]
	v_pk_mul_f32 v[78:79], v[78:79], v[136:137] op_sel_hi:[1,0]
	v_pk_mul_f32 v[76:77], v[76:77], v[136:137] op_sel_hi:[1,0]
	v_pk_mul_f32 v[86:87], v[86:87], v[136:137] op_sel_hi:[1,0]
	v_pk_mul_f32 v[84:85], v[84:85], v[136:137] op_sel_hi:[1,0]
	v_pk_mul_f32 v[94:95], v[94:95], v[136:137] op_sel_hi:[1,0]
	v_pk_mul_f32 v[92:93], v[92:93], v[136:137] op_sel_hi:[1,0]
	v_mul_f32_e32 v136, -1.0, v146
	v_fmamk_f32 v112, v112, 0x3f800000, v136
	v_exp_f32_e32 v142, v112
	v_fmamk_f32 v112, v113, 0x3f800000, v136
	v_exp_f32_e32 v143, v112
	v_fmamk_f32 v112, v114, 0x3f800000, v136
	v_exp_f32_e32 v144, v112
	v_fmamk_f32 v112, v115, 0x3f800000, v136
	v_exp_f32_e32 v145, v112
	v_fmamk_f32 v113, v120, 0x3f800000, v136
	v_add_f32_e32 v112, 0, v142
	v_exp_f32_e32 v120, v113
	v_fmamk_f32 v113, v121, 0x3f800000, v136
	v_add_f32_e32 v112, v143, v112
	v_exp_f32_e32 v121, v113
	v_fmamk_f32 v113, v122, 0x3f800000, v136
	v_add_f32_e32 v112, v144, v112
	v_exp_f32_e32 v122, v113
	v_fmamk_f32 v113, v123, 0x3f800000, v136
	v_add_f32_e32 v112, v145, v112
	v_exp_f32_e32 v123, v113
	v_add_f32_e32 v112, v120, v112
	v_add_f32_e32 v112, v121, v112
	v_add_f32_e32 v112, v122, v112
	v_add_f32_e32 v137, v123, v112
	v_fmamk_f32 v112, v116, 0x3f800000, v136
	v_exp_f32_e32 v112, v112
	v_fmamk_f32 v113, v117, 0x3f800000, v136
	v_exp_f32_e32 v113, v113
	v_fmamk_f32 v114, v118, 0x3f800000, v136
	v_exp_f32_e32 v114, v114
	v_fmamk_f32 v115, v119, 0x3f800000, v136
	v_exp_f32_e32 v115, v115
	v_add_f32_e32 v116, v112, v137
	v_add_f32_e32 v116, v113, v116
	v_add_f32_e32 v116, v114, v116
	v_add_f32_e32 v137, v115, v116
	v_fmamk_f32 v116, v124, 0x3f800000, v136
	v_exp_f32_e32 v116, v116
	v_fmamk_f32 v117, v125, 0x3f800000, v136
	v_exp_f32_e32 v117, v117
	v_fmamk_f32 v118, v126, 0x3f800000, v136
	v_exp_f32_e32 v118, v118
	v_fmac_f32_e32 v136, 1.0, v127
	v_exp_f32_e32 v119, v136
	v_add_f32_e32 v124, v116, v137
	v_add_f32_e32 v124, v117, v124
	v_add_f32_e32 v124, v118, v124
	v_add_f32_e32 v124, v119, v124
	v_sub_f32_e32 v136, v146, v164
	v_sub_f32_e32 v164, v164, v146
	v_sub_f32_e32 v165, v165, v146
	v_sub_f32_e32 v166, v166, v146
	v_sub_f32_e32 v167, v167, v146
	v_mov_b32_e32 v172, 0
	s_branch .LBB0_1946
.LBB0_1945:
	v_exp_f32_e32 v142, v112
	v_exp_f32_e32 v143, v113
	v_exp_f32_e32 v144, v114
	v_exp_f32_e32 v145, v115
	v_exp_f32_e32 v120, v120
	v_exp_f32_e32 v121, v121
	v_exp_f32_e32 v122, v122
	v_exp_f32_e32 v123, v123
	v_exp_f32_e32 v112, v116
	v_exp_f32_e32 v113, v117
	v_exp_f32_e32 v114, v118
	v_exp_f32_e32 v115, v119
	v_exp_f32_e32 v116, v124
	v_exp_f32_e32 v117, v125
	v_exp_f32_e32 v118, v126
	v_exp_f32_e32 v119, v127
	v_add_f32_e32 v124, v143, v142
	v_add_f32_e32 v124, v144, v124
	v_add_f32_e32 v124, v145, v124
	v_add_f32_e32 v124, v120, v124
	v_add_f32_e32 v124, v121, v124
	v_add_f32_e32 v124, v122, v124
	v_add_f32_e32 v124, v123, v124
	v_add_f32_e32 v124, v112, v124
	v_add_f32_e32 v124, v113, v124
	v_add_f32_e32 v124, v114, v124
	v_add_f32_e32 v124, v115, v124
	v_add_f32_e32 v124, v116, v124
	v_add_f32_e32 v124, v117, v124
	v_add_f32_e32 v124, v118, v124
	v_add_f32_e32 v124, v119, v124
.LBB0_1946:
	v_add_f32_e32 v134, v134, v124
	v_max_f32_e32 v124, v97, v96
	v_max3_f32 v124, v124, v98, v99
	v_max3_f32 v124, v124, v104, v105
	v_max3_f32 v124, v124, v106, v107
	v_max3_f32 v124, v124, v100, v101
	v_max3_f32 v124, v124, v102, v103
	v_max3_f32 v124, v124, v108, v109
	v_max3_f32 v124, v124, v110, v111
	v_sub_f32_e32 v125, v124, v173

	v_cmp_lt_f32_e32 vcc, s42, v125
	s_cbranch_vccz .LBB0_1948
	v_mov_b32_e32 v125, v124
	s_nop 1
	v_permlane16_swap_b32_e32 v124, v125
	v_max_f32_e32 v124, v125, v124
	v_mov_b32_e32 v125, v124
	s_nop 1
	v_permlane32_swap_b32_e32 v124, v125
	v_max3_f32 v125, v173, v124, v125
	v_sub_f32_e32 v124, v173, v125

	v_exp_f32_e32 v124, v124
	v_mul_f32_e32 v147, -1.0, v125
	v_fmamk_f32 v96, v96, 0x3f800000, v147
	v_sub_f32_e32 v137, v125, v168
	v_sub_f32_e32 v168, v168, v125
	v_sub_f32_e32 v169, v169, v125
	v_sub_f32_e32 v170, v170, v125
	v_sub_f32_e32 v171, v171, v125
	v_mov_b32_e32 v173, 0
	v_mul_f32_e32 v135, v135, v124
	v_pk_mul_f32 v[42:43], v[42:43], v[124:125] op_sel_hi:[1,0]
	v_pk_mul_f32 v[40:41], v[40:41], v[124:125] op_sel_hi:[1,0]
	v_pk_mul_f32 v[74:75], v[74:75], v[124:125] op_sel_hi:[1,0]
	v_pk_mul_f32 v[72:73], v[72:73], v[124:125] op_sel_hi:[1,0]
	v_pk_mul_f32 v[82:83], v[82:83], v[124:125] op_sel_hi:[1,0]
	v_pk_mul_f32 v[80:81], v[80:81], v[124:125] op_sel_hi:[1,0]
	v_pk_mul_f32 v[90:91], v[90:91], v[124:125] op_sel_hi:[1,0]
	v_pk_mul_f32 v[88:89], v[88:89], v[124:125] op_sel_hi:[1,0]
	v_exp_f32_e32 v124, v96
	v_fmamk_f32 v96, v97, 0x3f800000, v147
	v_exp_f32_e32 v125, v96
	v_fmamk_f32 v96, v98, 0x3f800000, v147
	v_exp_f32_e32 v126, v96
	v_fmamk_f32 v96, v99, 0x3f800000, v147
	v_exp_f32_e32 v127, v96
	v_fmamk_f32 v97, v104, 0x3f800000, v147
	v_add_f32_e32 v96, 0, v124
	v_exp_f32_e32 v146, v97
	v_fmamk_f32 v97, v105, 0x3f800000, v147
	v_add_f32_e32 v96, v125, v96
	v_exp_f32_e32 v105, v97
	v_fmamk_f32 v97, v106, 0x3f800000, v147
	v_add_f32_e32 v96, v126, v96
	v_exp_f32_e32 v106, v97
	v_fmamk_f32 v97, v107, 0x3f800000, v147
	v_add_f32_e32 v96, v127, v96
	v_exp_f32_e32 v107, v97
	v_fmamk_f32 v97, v100, 0x3f800000, v147
	v_add_f32_e32 v96, v146, v96
	v_exp_f32_e32 v97, v97
	v_fmamk_f32 v98, v101, 0x3f800000, v147
	v_add_f32_e32 v96, v105, v96
	v_exp_f32_e32 v98, v98
	v_fmamk_f32 v99, v102, 0x3f800000, v147
	v_add_f32_e32 v96, v106, v96
	v_exp_f32_e32 v99, v99
	v_fmamk_f32 v100, v103, 0x3f800000, v147
	v_add_f32_e32 v96, v107, v96
	v_exp_f32_e32 v100, v100
	v_fmamk_f32 v101, v108, 0x3f800000, v147
	v_fmamk_f32 v102, v109, 0x3f800000, v147
	v_fmamk_f32 v103, v110, 0x3f800000, v147
	v_fmac_f32_e32 v147, 1.0, v111
	v_add_f32_e32 v96, v97, v96
	v_exp_f32_e32 v101, v101
	v_exp_f32_e32 v102, v102
	v_exp_f32_e32 v103, v103
	v_exp_f32_e32 v104, v147
	v_add_f32_e32 v96, v98, v96
	v_add_f32_e32 v96, v99, v96
	s_branch .LBB0_1949
.LBB0_1948:
	v_exp_f32_e32 v124, v96
	v_exp_f32_e32 v125, v97
	v_exp_f32_e32 v126, v98
	v_exp_f32_e32 v127, v99
	v_exp_f32_e32 v146, v104
	v_exp_f32_e32 v105, v105
	v_exp_f32_e32 v106, v106
	v_exp_f32_e32 v107, v107
	v_exp_f32_e32 v97, v100
	v_exp_f32_e32 v98, v101
	v_exp_f32_e32 v99, v102
	v_exp_f32_e32 v100, v103
	v_exp_f32_e32 v101, v108
	v_exp_f32_e32 v102, v109
	v_exp_f32_e32 v103, v110
	v_exp_f32_e32 v104, v111
	v_add_f32_e32 v96, v125, v124
	v_add_f32_e32 v96, v126, v96
	v_add_f32_e32 v96, v127, v96
	v_add_f32_e32 v96, v146, v96
	v_add_f32_e32 v96, v105, v96
	v_add_f32_e32 v96, v106, v96
	v_add_f32_e32 v96, v107, v96
	v_add_f32_e32 v96, v97, v96
	v_add_f32_e32 v96, v98, v96
	v_add_f32_e32 v96, v99, v96

.LBB0_1950:
	s_andn2_saveexec_b64 s[10:11], s[10:11]
	s_cbranch_execz .LBB0_1958
	v_mov_b32_e32 v96, v186
	s_nop 0
	v_bfe_u32 v126, v96, 4, 2
	v_and_b32_e32 v113, 15, v96
	v_lshlrev_b32_e32 v112, 4, v126
	v_mad_u32_u24 v127, v113, s36, v112
	ds_read_b128 v[96:99], v127
	ds_read_b128 v[104:107], v127 offset:64
	ds_read_b128 v[108:111], v127 offset:3392
	ds_read_b128 v[118:121], v127 offset:6720
	ds_read_b128 v[122:125], v127 offset:10048
	s_waitcnt lgkmcnt(4)
	v_mfma_f32_16x16x32_bf16 v[100:103], v[96:99], v[16:19], 0
	v_mfma_f32_16x16x32_bf16 v[96:99], v[96:99], v[8:11], 0
	s_waitcnt lgkmcnt(3)
	v_mfma_f32_16x16x32_bf16 v[100:103], v[104:107], v[0:3], v[100:103]
	v_mfma_f32_16x16x32_bf16 v[96:99], v[104:107], v[12:15], v[96:99]
	ds_read_b128 v[104:107], v127 offset:128
	s_waitcnt lgkmcnt(0)
	v_mfma_f32_16x16x32_bf16 v[114:117], v[104:107], v[4:7], v[100:103]
	s_nop 3
	ds_read_b128 v[100:103], v127 offset:3328
	v_mfma_f32_16x16x32_bf16 v[96:99], v[104:107], v[20:23], v[96:99]
	s_waitcnt lgkmcnt(0)
	v_mfma_f32_16x16x32_bf16 v[104:107], v[100:103], v[16:19], 0
	v_mfma_f32_16x16x32_bf16 v[100:103], v[100:103], v[8:11], 0
	v_mfma_f32_16x16x32_bf16 v[104:107], v[108:111], v[0:3], v[104:107]
	v_mfma_f32_16x16x32_bf16 v[100:103], v[108:111], v[12:15], v[100:103]
	ds_read_b128 v[108:111], v127 offset:3456
	s_waitcnt lgkmcnt(0)
	v_mfma_f32_16x16x32_bf16 v[144:147], v[108:111], v[4:7], v[104:107]
	s_nop 3
	ds_read_b128 v[104:107], v127 offset:6656
	v_mfma_f32_16x16x32_bf16 v[100:103], v[108:111], v[20:23], v[100:103]
	s_waitcnt lgkmcnt(0)
	v_mfma_f32_16x16x32_bf16 v[108:111], v[104:107], v[16:19], 0
	v_mfma_f32_16x16x32_bf16 v[104:107], v[104:107], v[8:11], 0
	v_mfma_f32_16x16x32_bf16 v[108:111], v[118:121], v[0:3], v[108:111]
	v_mfma_f32_16x16x32_bf16 v[104:107], v[118:121], v[12:15], v[104:107]
	ds_read_b128 v[118:121], v127 offset:6784
	s_waitcnt lgkmcnt(0)
	v_mfma_f32_16x16x32_bf16 v[148:151], v[118:121], v[4:7], v[108:111]
	s_nop 3
	ds_read_b128 v[108:111], v127 offset:9984
	v_mfma_f32_16x16x32_bf16 v[104:107], v[118:121], v[20:23], v[104:107]
	s_waitcnt lgkmcnt(0)
	v_mfma_f32_16x16x32_bf16 v[118:121], v[108:111], v[16:19], 0
	v_mfma_f32_16x16x32_bf16 v[108:111], v[108:111], v[8:11], 0
	v_mfma_f32_16x16x32_bf16 v[118:121], v[122:125], v[0:3], v[118:121]
	v_mfma_f32_16x16x32_bf16 v[108:111], v[122:125], v[12:15], v[108:111]
	ds_read_b128 v[122:125], v127 offset:10112
	s_waitcnt lgkmcnt(0)
	v_mfma_f32_16x16x32_bf16 v[152:155], v[122:125], v[4:7], v[118:121]
	s_nop 3
	v_lshlrev_b32_e32 v118, 3, v126
	v_sub_u32_e32 v142, v132, v118
	v_mfma_f32_16x16x32_bf16 v[108:111], v[122:125], v[20:23], v[108:111]
	v_add_u32_e32 v125, -16, v142
	v_cmp_lt_i32_e32 vcc, -1, v125
	s_nop 1
	v_cndmask_b32_e32 v118, v207, v114, vcc
	v_cmp_lt_i32_e32 vcc, 0, v125
	s_nop 1
	v_cndmask_b32_e32 v120, v207, v115, vcc
	v_cmp_lt_i32_e32 vcc, 1, v125
	v_max_f32_e32 v143, v120, v120
	s_nop 0
	v_cndmask_b32_e32 v122, v207, v116, vcc
	v_cmp_lt_i32_e32 vcc, 2, v125
	s_nop 1
	v_cndmask_b32_e32 v124, v207, v117, vcc
	v_cmp_lt_i32_e32 vcc, 3, v125
	s_nop 1
	v_cndmask_b32_e32 v126, v207, v144, vcc
	v_cmp_lt_i32_e32 vcc, 4, v125
	v_max_f32_e32 v144, v118, v118
	v_max_f32_e32 v143, v144, v143
	v_cndmask_b32_e32 v127, v207, v145, vcc
	v_cmp_lt_i32_e32 vcc, 5, v125
	v_max3_f32 v143, v143, v122, v124
	v_max3_f32 v143, v143, v126, v127
	v_cndmask_b32_e32 v140, v207, v146, vcc
	v_cmp_lt_i32_e32 vcc, 6, v125
	s_nop 1
	v_cndmask_b32_e32 v141, v207, v147, vcc
	v_cmp_lt_i32_e32 vcc, 31, v125
	v_max3_f32 v143, v143, v140, v141
	s_nop 0
	v_cndmask_b32_e32 v114, v207, v148, vcc
	v_cmp_lt_i32_e32 vcc, 32, v125
	s_nop 1
	v_cndmask_b32_e32 v115, v207, v149, vcc
	v_cmp_lt_i32_e32 vcc, 33, v125
	v_max3_f32 v143, v143, v114, v115
	s_nop 0
	v_cndmask_b32_e32 v116, v207, v150, vcc
	v_cmp_lt_i32_e32 vcc, 34, v125
	s_nop 1
	v_cndmask_b32_e32 v117, v207, v151, vcc
	v_cmp_lt_i32_e32 vcc, 35, v125
	v_max3_f32 v143, v143, v116, v117
	s_nop 0
	v_cndmask_b32_e32 v119, v207, v152, vcc
	v_cmp_lt_i32_e32 vcc, 36, v125
	s_nop 1
	v_cndmask_b32_e32 v121, v207, v153, vcc
	v_cmp_lt_i32_e32 vcc, 37, v125
	v_max3_f32 v143, v143, v119, v121
	s_nop 0
	v_cndmask_b32_e32 v123, v207, v154, vcc
	v_cmp_lt_i32_e32 vcc, 38, v125
	s_nop 1
	v_cndmask_b32_e32 v125, v207, v155, vcc
	v_max3_f32 v143, v143, v123, v125
	v_sub_f32_e32 v144, v143, v136
	v_mul_f32_e32 v144, 1.0, v144
	v_cmp_lt_f32_e32 vcc, s42, v144
	s_cbranch_vccz .LBB0_1953
	v_mov_b32_e32 v144, v143
	s_nop 1
	v_permlane16_swap_b32_e32 v143, v144
	v_max_f32_e32 v143, v144, v143
	v_mov_b32_e32 v144, v143
	s_nop 1
	v_permlane32_swap_b32_e32 v143, v144
	v_max3_f32 v144, v136, v143, v144
	v_sub_f32_e32 v136, v136, v144
	v_mul_f32_e32 v136, 1.0, v136
	v_exp_f32_e32 v136, v136
	v_mov_b32_e32 v145, v137
	v_mul_f32_e32 v134, v134, v136
	v_pk_mul_f32 v[50:51], v[50:51], v[136:137] op_sel_hi:[1,0]
	v_pk_mul_f32 v[48:49], v[48:49], v[136:137] op_sel_hi:[1,0]
	v_pk_mul_f32 v[78:79], v[78:79], v[136:137] op_sel_hi:[1,0]
	v_pk_mul_f32 v[76:77], v[76:77], v[136:137] op_sel_hi:[1,0]
	v_pk_mul_f32 v[86:87], v[86:87], v[136:137] op_sel_hi:[1,0]
	v_pk_mul_f32 v[84:85], v[84:85], v[136:137] op_sel_hi:[1,0]
	v_pk_mul_f32 v[94:95], v[94:95], v[136:137] op_sel_hi:[1,0]
	v_pk_mul_f32 v[92:93], v[92:93], v[136:137] op_sel_hi:[1,0]
	v_mul_f32_e32 v136, -1.0, v144
	v_fmamk_f32 v118, v118, 0x3f800000, v136
	v_exp_f32_e32 v118, v118
	v_fmamk_f32 v120, v120, 0x3f800000, v136
	v_exp_f32_e32 v120, v120
	v_fmamk_f32 v122, v122, 0x3f800000, v136
	v_exp_f32_e32 v122, v122
	v_fmamk_f32 v124, v124, 0x3f800000, v136
	v_exp_f32_e32 v124, v124
	v_fmamk_f32 v126, v126, 0x3f800000, v136
	v_add_f32_e32 v137, 0, v118
	v_exp_f32_e32 v126, v126
	v_fmamk_f32 v127, v127, 0x3f800000, v136
	v_add_f32_e32 v137, v120, v137
	v_exp_f32_e32 v127, v127
	v_fmamk_f32 v140, v140, 0x3f800000, v136
	v_add_f32_e32 v137, v122, v137
	v_exp_f32_e32 v140, v140
	v_fmamk_f32 v141, v141, 0x3f800000, v136
	v_add_f32_e32 v137, v124, v137
	v_exp_f32_e32 v141, v141
	v_fmamk_f32 v114, v114, 0x3f800000, v136
	v_add_f32_e32 v137, v126, v137
	v_exp_f32_e32 v114, v114
	v_fmamk_f32 v115, v115, 0x3f800000, v136
	v_add_f32_e32 v137, v127, v137
	v_exp_f32_e32 v115, v115
	v_fmamk_f32 v116, v116, 0x3f800000, v136
	v_add_f32_e32 v137, v140, v137
	v_exp_f32_e32 v116, v116
	v_fmamk_f32 v117, v117, 0x3f800000, v136
	v_add_f32_e32 v137, v141, v137
	v_exp_f32_e32 v117, v117
	v_fmamk_f32 v119, v119, 0x3f800000, v136
	v_add_f32_e32 v137, v114, v137
	v_exp_f32_e32 v119, v119
	v_fmamk_f32 v121, v121, 0x3f800000, v136
	v_add_f32_e32 v137, v115, v137
	v_exp_f32_e32 v121, v121
	v_fmamk_f32 v123, v123, 0x3f800000, v136
	v_add_f32_e32 v137, v116, v137
	v_exp_f32_e32 v123, v123
	v_fmac_f32_e32 v136, 1.0, v125
	v_add_f32_e32 v137, v117, v137
	v_exp_f32_e32 v125, v136
	v_add_f32_e32 v136, v119, v137
	v_add_f32_e32 v136, v121, v136
	v_add_f32_e32 v136, v123, v136
	v_add_f32_e32 v143, v125, v136
	v_mov_b64_e32 v[136:137], v[144:145]
	s_branch .LBB0_1954
.LBB0_1953:
	v_mul_f32_e32 v143, -1.0, v136
	v_fmamk_f32 v118, v118, 0x3f800000, v143
	v_exp_f32_e32 v118, v118
	v_fmamk_f32 v120, v120, 0x3f800000, v143
	v_exp_f32_e32 v120, v120
	v_fmamk_f32 v122, v122, 0x3f800000, v143
	v_exp_f32_e32 v122, v122
	v_fmamk_f32 v124, v124, 0x3f800000, v143
	v_exp_f32_e32 v124, v124
	v_fmamk_f32 v126, v126, 0x3f800000, v143
	v_fmamk_f32 v127, v127, 0x3f800000, v143
	v_fmamk_f32 v140, v140, 0x3f800000, v143
	v_fmamk_f32 v141, v141, 0x3f800000, v143
	v_fmamk_f32 v114, v114, 0x3f800000, v143
	v_fmamk_f32 v115, v115, 0x3f800000, v143
	v_fmamk_f32 v116, v116, 0x3f800000, v143
	v_fmamk_f32 v117, v117, 0x3f800000, v143
	v_fmamk_f32 v119, v119, 0x3f800000, v143
	v_fmamk_f32 v121, v121, 0x3f800000, v143
	v_fmamk_f32 v123, v123, 0x3f800000, v143
	v_fmac_f32_e32 v143, 1.0, v125
	v_exp_f32_e32 v126, v126
	v_exp_f32_e32 v125, v143
	v_add_f32_e32 v143, 0, v118
	v_exp_f32_e32 v127, v127
	v_add_f32_e32 v143, v120, v143
	v_exp_f32_e32 v140, v140
	v_add_f32_e32 v143, v122, v143
	v_exp_f32_e32 v141, v141
	v_add_f32_e32 v143, v124, v143
	v_exp_f32_e32 v114, v114
	v_add_f32_e32 v143, v143, v126
	v_exp_f32_e32 v115, v115
	v_add_f32_e32 v143, v127, v143
	v_exp_f32_e32 v116, v116
	v_add_f32_e32 v143, v140, v143
	v_exp_f32_e32 v117, v117
	v_add_f32_e32 v143, v141, v143
	v_exp_f32_e32 v119, v119
	v_add_f32_e32 v143, v143, v114
	v_exp_f32_e32 v121, v121
	v_add_f32_e32 v143, v115, v143
	v_exp_f32_e32 v123, v123
	v_add_f32_e32 v143, v116, v143
	v_add_f32_e32 v143, v117, v143
	v_add_f32_e32 v143, v143, v119
	v_add_f32_e32 v143, v121, v143
	v_add_f32_e32 v143, v123, v143
	v_add_f32_e32 v143, v125, v143
.LBB0_1954:
	v_cmp_lt_i32_e32 vcc, -1, v142
	v_add_f32_e32 v134, v134, v143
	s_nop 0
	v_cndmask_b32_e32 v150, v207, v96, vcc
	v_cmp_lt_i32_e32 vcc, 0, v142
	s_nop 1
	v_cndmask_b32_e32 v149, v207, v97, vcc
	v_cmp_lt_i32_e32 vcc, 1, v142
	s_nop 1
	v_cndmask_b32_e32 v148, v207, v98, vcc
	v_cmp_lt_i32_e32 vcc, 2, v142
	s_nop 1
	v_cndmask_b32_e32 v147, v207, v99, vcc
	v_cmp_lt_i32_e32 vcc, 3, v142
	s_nop 1
	v_cndmask_b32_e32 v146, v207, v100, vcc
	v_cmp_lt_i32_e32 vcc, 4, v142
	s_nop 1
	v_cndmask_b32_e32 v145, v207, v101, vcc
	v_cmp_lt_i32_e32 vcc, 5, v142
	v_max_f32_e32 v101, v149, v149
	s_nop 0
	v_cndmask_b32_e32 v144, v207, v102, vcc
	v_cmp_lt_i32_e32 vcc, 6, v142
	s_nop 1
	v_cndmask_b32_e32 v143, v207, v103, vcc
	v_cmp_lt_i32_e32 vcc, 31, v142
	v_max_f32_e32 v103, v150, v150
	v_max_f32_e32 v101, v103, v101
	v_cndmask_b32_e32 v97, v207, v104, vcc
	v_cmp_lt_i32_e32 vcc, 32, v142
	v_max3_f32 v101, v101, v148, v147
	v_max3_f32 v101, v101, v146, v145
	v_cndmask_b32_e32 v98, v207, v105, vcc
	v_cmp_lt_i32_e32 vcc, 33, v142
	v_max3_f32 v101, v101, v144, v143
	v_max3_f32 v101, v101, v97, v98
	v_cndmask_b32_e32 v99, v207, v106, vcc
	v_cmp_lt_i32_e32 vcc, 34, v142
	s_nop 1
	v_cndmask_b32_e32 v100, v207, v107, vcc
	v_cmp_lt_i32_e32 vcc, 35, v142
	v_max3_f32 v101, v101, v99, v100
	s_nop 0
	v_cndmask_b32_e32 v102, v207, v108, vcc
	v_cmp_lt_i32_e32 vcc, 36, v142
	s_nop 1
	v_cndmask_b32_e32 v104, v207, v109, vcc
	v_cmp_lt_i32_e32 vcc, 37, v142
	v_max3_f32 v101, v101, v102, v104
	s_nop 0
	v_cndmask_b32_e32 v106, v207, v110, vcc
	v_cmp_lt_i32_e32 vcc, 38, v142
	s_nop 1
	v_cndmask_b32_e32 v96, v207, v111, vcc
	v_max3_f32 v101, v101, v106, v96
	v_sub_f32_e32 v103, v101, v137
	v_mul_f32_e32 v103, 1.0, v103
	v_cmp_lt_f32_e32 vcc, s42, v103
	s_cbranch_vccz .LBB0_1956
	v_mov_b32_e32 v103, v101
	s_nop 1
	v_permlane16_swap_b32_e32 v101, v103
	v_max_f32_e32 v101, v103, v101
	v_mov_b32_e32 v103, v101
	s_nop 1
	v_permlane32_swap_b32_e32 v101, v103
	v_max3_f32 v101, v137, v101, v103
	v_sub_f32_e32 v103, v137, v101
	v_mul_f32_e32 v103, 1.0, v103
	v_exp_f32_e32 v108, v103
	v_mov_b32_e32 v137, v101
	v_mul_f32_e32 v135, v135, v108
	v_pk_mul_f32 v[42:43], v[42:43], v[108:109] op_sel_hi:[1,0]
	v_pk_mul_f32 v[40:41], v[40:41], v[108:109] op_sel_hi:[1,0]
	v_pk_mul_f32 v[74:75], v[74:75], v[108:109] op_sel_hi:[1,0]
	v_pk_mul_f32 v[72:73], v[72:73], v[108:109] op_sel_hi:[1,0]
	v_pk_mul_f32 v[82:83], v[82:83], v[108:109] op_sel_hi:[1,0]
	v_pk_mul_f32 v[80:81], v[80:81], v[108:109] op_sel_hi:[1,0]
	v_pk_mul_f32 v[90:91], v[90:91], v[108:109] op_sel_hi:[1,0]
	v_pk_mul_f32 v[88:89], v[88:89], v[108:109] op_sel_hi:[1,0]
	v_mul_f32_e32 v108, -1.0, v101
	v_fmamk_f32 v101, v150, 0x3f800000, v108
	v_exp_f32_e32 v101, v101
	v_fmamk_f32 v103, v149, 0x3f800000, v108
	v_exp_f32_e32 v103, v103
	v_fmamk_f32 v105, v148, 0x3f800000, v108
	v_exp_f32_e32 v105, v105
	v_fmamk_f32 v107, v147, 0x3f800000, v108
	v_exp_f32_e32 v107, v107
	v_add_f32_e32 v109, v103, v101
	v_add_f32_e32 v109, v105, v109
	v_add_f32_e32 v147, v107, v109
	v_fmamk_f32 v109, v146, 0x3f800000, v108
	v_exp_f32_e32 v109, v109
	v_fmamk_f32 v110, v145, 0x3f800000, v108
	v_exp_f32_e32 v110, v110
	v_fmamk_f32 v111, v144, 0x3f800000, v108
	v_exp_f32_e32 v111, v111
	v_fmamk_f32 v142, v143, 0x3f800000, v108
	v_exp_f32_e32 v142, v142
	v_fmamk_f32 v97, v97, 0x3f800000, v108
	v_add_f32_e32 v143, v109, v147
	v_exp_f32_e32 v97, v97
	v_fmamk_f32 v98, v98, 0x3f800000, v108
	v_add_f32_e32 v143, v110, v143
	v_exp_f32_e32 v98, v98
	v_fmamk_f32 v99, v99, 0x3f800000, v108
	v_add_f32_e32 v143, v111, v143
	v_exp_f32_e32 v99, v99
	v_fmamk_f32 v100, v100, 0x3f800000, v108
	v_add_f32_e32 v143, v142, v143
	v_exp_f32_e32 v100, v100
	v_fmamk_f32 v102, v102, 0x3f800000, v108
	v_add_f32_e32 v143, v97, v143
	v_exp_f32_e32 v102, v102
	v_fmamk_f32 v104, v104, 0x3f800000, v108
	v_fmamk_f32 v106, v106, 0x3f800000, v108
	v_fmac_f32_e32 v108, 1.0, v96
	v_add_f32_e32 v143, v98, v143
	v_exp_f32_e32 v104, v104
	v_exp_f32_e32 v106, v106
	v_exp_f32_e32 v108, v108
	v_add_f32_e32 v143, v99, v143
	v_add_f32_e32 v143, v100, v143
	v_add_f32_e32 v96, v102, v143
	s_branch .LBB0_1957
.LBB0_1956:
	v_mul_f32_e32 v108, -1.0, v137
	v_fmamk_f32 v101, v150, 0x3f800000, v108
	v_exp_f32_e32 v101, v101
	v_fmamk_f32 v103, v149, 0x3f800000, v108
	v_exp_f32_e32 v103, v103
	v_fmamk_f32 v105, v148, 0x3f800000, v108
	v_exp_f32_e32 v105, v105
	v_fmamk_f32 v107, v147, 0x3f800000, v108
	v_exp_f32_e32 v107, v107
	v_fmamk_f32 v109, v146, 0x3f800000, v108
	v_exp_f32_e32 v109, v109
	v_fmamk_f32 v110, v145, 0x3f800000, v108
	v_fmamk_f32 v111, v144, 0x3f800000, v108
	v_fmamk_f32 v142, v143, 0x3f800000, v108
	v_fmamk_f32 v97, v97, 0x3f800000, v108
	v_fmamk_f32 v98, v98, 0x3f800000, v108
	v_fmamk_f32 v99, v99, 0x3f800000, v108
	v_fmamk_f32 v100, v100, 0x3f800000, v108
	v_fmamk_f32 v102, v102, 0x3f800000, v108
	v_fmamk_f32 v104, v104, 0x3f800000, v108
	v_fmamk_f32 v106, v106, 0x3f800000, v108
	v_fmac_f32_e32 v108, 1.0, v96
	v_add_f32_e32 v96, 0, v101
	v_exp_f32_e32 v110, v110
	v_add_f32_e32 v96, v103, v96
	v_exp_f32_e32 v111, v111
	v_add_f32_e32 v96, v105, v96
	v_exp_f32_e32 v142, v142
	v_add_f32_e32 v96, v107, v96
	v_exp_f32_e32 v97, v97
	v_add_f32_e32 v96, v109, v96
	v_exp_f32_e32 v98, v98
	v_add_f32_e32 v96, v110, v96
	v_exp_f32_e32 v99, v99
	v_add_f32_e32 v96, v111, v96
	v_exp_f32_e32 v100, v100
	v_add_f32_e32 v96, v142, v96
	v_exp_f32_e32 v102, v102
	v_add_f32_e32 v96, v97, v96
	v_add_f32_e32 v96, v98, v96
	v_add_f32_e32 v96, v99, v96
	v_add_f32_e32 v96, v100, v96
	v_exp_f32_e32 v104, v104
	v_exp_f32_e32 v106, v106
	v_exp_f32_e32 v108, v108
	v_add_f32_e32 v96, v102, v96

.LBB0_1959:
	s_or_b64 exec, exec, s[8:9]
	s_add_i32 s3, s2, 0xffffff80
	v_cmp_le_i32_e32 vcc, s3, v133
	s_and_saveexec_b64 s[8:9], vcc
	s_cbranch_execz .LBB0_1938
	s_add_i32 s3, s2, 0xffffffbf
	v_cmp_le_i32_e32 vcc, s3, v139
	s_and_saveexec_b64 s[10:11], vcc
	s_xor_b64 s[10:11], exec, s[10:11]
	s_cbranch_execz .LBB0_1968
	ds_read_b128 v[96:99], v244 offset:22528
	ds_read_b128 v[104:107], v244 offset:22592
	ds_read_b128 v[108:111], v244 offset:25920
	ds_read_b128 v[116:119], v244 offset:29248
	ds_read_b128 v[124:127], v244 offset:29312
	ds_read_b128 v[142:145], v244 offset:32576
	s_waitcnt lgkmcnt(5)
	v_mfma_f32_16x16x32_bf16 v[100:103], v[96:99], v[16:19], v[164:167]
	v_mfma_f32_16x16x32_bf16 v[96:99], v[96:99], v[8:11], v[168:171]
	s_waitcnt lgkmcnt(4)
	v_mfma_f32_16x16x32_bf16 v[100:103], v[104:107], v[0:3], v[100:103]
	v_mfma_f32_16x16x32_bf16 v[96:99], v[104:107], v[12:15], v[96:99]
	ds_read_b128 v[104:107], v244 offset:22656
	s_waitcnt lgkmcnt(0)
	v_mfma_f32_16x16x32_bf16 v[112:115], v[104:107], v[4:7], v[100:103]
	s_nop 3
	ds_read_b128 v[100:103], v244 offset:25856
	v_mfma_f32_16x16x32_bf16 v[96:99], v[104:107], v[20:23], v[96:99]
	s_waitcnt lgkmcnt(0)
	v_mfma_f32_16x16x32_bf16 v[104:107], v[100:103], v[16:19], v[164:167]
	v_mfma_f32_16x16x32_bf16 v[100:103], v[100:103], v[8:11], v[168:171]
	v_mfma_f32_16x16x32_bf16 v[104:107], v[108:111], v[0:3], v[104:107]
	v_mfma_f32_16x16x32_bf16 v[100:103], v[108:111], v[12:15], v[100:103]
	ds_read_b128 v[108:111], v244 offset:25984
	s_waitcnt lgkmcnt(0)
	v_mfma_f32_16x16x32_bf16 v[120:123], v[108:111], v[4:7], v[104:107]
	v_mfma_f32_16x16x32_bf16 v[104:107], v[108:111], v[20:23], v[100:103]
	s_nop 3
	ds_read_b128 v[100:103], v244 offset:29184
	s_waitcnt lgkmcnt(0)
	v_mfma_f32_16x16x32_bf16 v[108:111], v[100:103], v[16:19], v[164:167]
	v_mfma_f32_16x16x32_bf16 v[100:103], v[100:103], v[8:11], v[168:171]
	v_mfma_f32_16x16x32_bf16 v[108:111], v[116:119], v[0:3], v[108:111]
	v_mfma_f32_16x16x32_bf16 v[100:103], v[116:119], v[12:15], v[100:103]
	v_mfma_f32_16x16x32_bf16 v[116:119], v[124:127], v[4:7], v[108:111]
	s_nop 5
	ds_read_b128 v[108:111], v244 offset:32512
	v_mfma_f32_16x16x32_bf16 v[100:103], v[124:127], v[20:23], v[100:103]
	s_waitcnt lgkmcnt(0)
	v_mfma_f32_16x16x32_bf16 v[124:127], v[108:111], v[16:19], v[164:167]
	v_mfma_f32_16x16x32_bf16 v[108:111], v[108:111], v[8:11], v[168:171]
	v_mfma_f32_16x16x32_bf16 v[124:127], v[142:145], v[0:3], v[124:127]
	v_mfma_f32_16x16x32_bf16 v[108:111], v[142:145], v[12:15], v[108:111]
	ds_read_b128 v[142:145], v244 offset:32640
	s_waitcnt lgkmcnt(0)
	v_mfma_f32_16x16x32_bf16 v[124:127], v[142:145], v[4:7], v[124:127]
	v_mfma_f32_16x16x32_bf16 v[108:111], v[142:145], v[20:23], v[108:111]
	v_max_f32_e32 v142, v113, v112
	v_max3_f32 v142, v142, v114, v115
	v_max3_f32 v142, v142, v120, v121
	v_max3_f32 v142, v142, v122, v123
	v_max3_f32 v142, v142, v116, v117
	v_max3_f32 v142, v142, v118, v119
	s_nop 0
	v_max3_f32 v142, v142, v124, v125
	v_max3_f32 v142, v142, v126, v127
	v_sub_f32_e32 v143, v142, v172

	v_cmp_lt_f32_e32 vcc, s42, v143
	s_cbranch_vccz .LBB0_1963
	v_mov_b32_e32 v143, v142
	s_nop 1
	v_permlane16_swap_b32_e32 v142, v143
	v_max_f32_e32 v142, v143, v142
	v_mov_b32_e32 v143, v142
	s_nop 1
	v_permlane32_swap_b32_e32 v142, v143
	v_max3_f32 v146, v172, v142, v143
	v_sub_f32_e32 v136, v172, v146

	v_exp_f32_e32 v136, v136
	v_mov_b32_e32 v147, v137
	v_mul_f32_e32 v134, v134, v136
	v_pk_mul_f32 v[50:51], v[50:51], v[136:137] op_sel_hi:[1,0]
	v_pk_mul_f32 v[48:49], v[48:49], v[136:137] op_sel_hi:[1,0]
	v_pk_mul_f32 v[78:79], v[78:79], v[136:137] op_sel_hi:[1,0]
	v_pk_mul_f32 v[76:77], v[76:77], v[136:137] op_sel_hi:[1,0]
	v_pk_mul_f32 v[86:87], v[86:87], v[136:137] op_sel_hi:[1,0]
	v_pk_mul_f32 v[84:85], v[84:85], v[136:137] op_sel_hi:[1,0]
	v_pk_mul_f32 v[94:95], v[94:95], v[136:137] op_sel_hi:[1,0]
	v_pk_mul_f32 v[92:93], v[92:93], v[136:137] op_sel_hi:[1,0]
	v_mul_f32_e32 v136, -1.0, v146
	v_fmamk_f32 v112, v112, 0x3f800000, v136
	v_exp_f32_e32 v142, v112
	v_fmamk_f32 v112, v113, 0x3f800000, v136
	v_exp_f32_e32 v143, v112
	v_fmamk_f32 v112, v114, 0x3f800000, v136
	v_exp_f32_e32 v144, v112
	v_fmamk_f32 v112, v115, 0x3f800000, v136
	v_exp_f32_e32 v145, v112
	v_fmamk_f32 v113, v120, 0x3f800000, v136
	v_add_f32_e32 v112, 0, v142
	v_exp_f32_e32 v120, v113
	v_fmamk_f32 v113, v121, 0x3f800000, v136
	v_add_f32_e32 v112, v143, v112
	v_exp_f32_e32 v121, v113
	v_fmamk_f32 v113, v122, 0x3f800000, v136
	v_add_f32_e32 v112, v144, v112
	v_exp_f32_e32 v122, v113
	v_fmamk_f32 v113, v123, 0x3f800000, v136
	v_add_f32_e32 v112, v145, v112
	v_exp_f32_e32 v123, v113
	v_add_f32_e32 v112, v120, v112
	v_add_f32_e32 v112, v121, v112
	v_add_f32_e32 v112, v122, v112
	v_add_f32_e32 v137, v123, v112
	v_fmamk_f32 v112, v116, 0x3f800000, v136
	v_exp_f32_e32 v112, v112
	v_fmamk_f32 v113, v117, 0x3f800000, v136
	v_exp_f32_e32 v113, v113
	v_fmamk_f32 v114, v118, 0x3f800000, v136
	v_exp_f32_e32 v114, v114
	v_fmamk_f32 v115, v119, 0x3f800000, v136
	v_exp_f32_e32 v115, v115
	v_add_f32_e32 v116, v112, v137
	v_add_f32_e32 v116, v113, v116
	v_add_f32_e32 v116, v114, v116
	v_add_f32_e32 v137, v115, v116
	v_fmamk_f32 v116, v124, 0x3f800000, v136
	v_exp_f32_e32 v116, v116
	v_fmamk_f32 v117, v125, 0x3f800000, v136
	v_exp_f32_e32 v117, v117
	v_fmamk_f32 v118, v126, 0x3f800000, v136
	v_exp_f32_e32 v118, v118
	v_fmac_f32_e32 v136, 1.0, v127
	v_exp_f32_e32 v119, v136
	v_add_f32_e32 v124, v116, v137
	v_add_f32_e32 v124, v117, v124
	v_add_f32_e32 v124, v118, v124
	v_add_f32_e32 v124, v119, v124
	v_sub_f32_e32 v136, v146, v164
	v_sub_f32_e32 v164, v164, v146
	v_sub_f32_e32 v165, v165, v146
	v_sub_f32_e32 v166, v166, v146
	v_sub_f32_e32 v167, v167, v146
	v_mov_b32_e32 v172, 0
	s_branch .LBB0_1964

.LBB0_1968:
	s_andn2_saveexec_b64 s[10:11], s[10:11]
	s_cbranch_execz .LBB0_1937
	v_mov_b32_e32 v96, v186
	s_nop 0
	v_bfe_u32 v126, v96, 4, 2
	v_and_b32_e32 v113, 15, v96
	v_lshlrev_b32_e32 v112, 4, v126
	v_mad_u32_u24 v127, v113, s36, v112
	ds_read_b128 v[96:99], v127 offset:22528
	ds_read_b128 v[104:107], v127 offset:22592
	ds_read_b128 v[108:111], v127 offset:25920
	ds_read_b128 v[118:121], v127 offset:29248
	ds_read_b128 v[122:125], v127 offset:32576
	s_waitcnt lgkmcnt(4)
	v_mfma_f32_16x16x32_bf16 v[100:103], v[96:99], v[16:19], 0
	v_mfma_f32_16x16x32_bf16 v[96:99], v[96:99], v[8:11], 0
	s_waitcnt lgkmcnt(3)
	v_mfma_f32_16x16x32_bf16 v[100:103], v[104:107], v[0:3], v[100:103]
	v_mfma_f32_16x16x32_bf16 v[96:99], v[104:107], v[12:15], v[96:99]
	ds_read_b128 v[104:107], v127 offset:22656
	s_waitcnt lgkmcnt(0)
	v_mfma_f32_16x16x32_bf16 v[114:117], v[104:107], v[4:7], v[100:103]
	s_nop 3
	ds_read_b128 v[100:103], v127 offset:25856
	v_mfma_f32_16x16x32_bf16 v[96:99], v[104:107], v[20:23], v[96:99]
	s_waitcnt lgkmcnt(0)
	v_mfma_f32_16x16x32_bf16 v[104:107], v[100:103], v[16:19], 0
	v_mfma_f32_16x16x32_bf16 v[100:103], v[100:103], v[8:11], 0
	v_mfma_f32_16x16x32_bf16 v[104:107], v[108:111], v[0:3], v[104:107]
	v_mfma_f32_16x16x32_bf16 v[100:103], v[108:111], v[12:15], v[100:103]
	ds_read_b128 v[108:111], v127 offset:25984
	s_waitcnt lgkmcnt(0)
	v_mfma_f32_16x16x32_bf16 v[144:147], v[108:111], v[4:7], v[104:107]
	s_nop 3
	ds_read_b128 v[104:107], v127 offset:29184
	v_mfma_f32_16x16x32_bf16 v[100:103], v[108:111], v[20:23], v[100:103]
	s_waitcnt lgkmcnt(0)
	v_mfma_f32_16x16x32_bf16 v[108:111], v[104:107], v[16:19], 0
	v_mfma_f32_16x16x32_bf16 v[104:107], v[104:107], v[8:11], 0
	v_mfma_f32_16x16x32_bf16 v[108:111], v[118:121], v[0:3], v[108:111]
	v_mfma_f32_16x16x32_bf16 v[104:107], v[118:121], v[12:15], v[104:107]
	ds_read_b128 v[118:121], v127 offset:29312
	s_waitcnt lgkmcnt(0)
	v_mfma_f32_16x16x32_bf16 v[148:151], v[118:121], v[4:7], v[108:111]
	s_nop 3
	ds_read_b128 v[108:111], v127 offset:32512
	v_mfma_f32_16x16x32_bf16 v[104:107], v[118:121], v[20:23], v[104:107]
	s_waitcnt lgkmcnt(0)
	v_mfma_f32_16x16x32_bf16 v[118:121], v[108:111], v[16:19], 0
	v_mfma_f32_16x16x32_bf16 v[108:111], v[108:111], v[8:11], 0
	v_mfma_f32_16x16x32_bf16 v[118:121], v[122:125], v[0:3], v[118:121]
	v_mfma_f32_16x16x32_bf16 v[108:111], v[122:125], v[12:15], v[108:111]
	ds_read_b128 v[122:125], v127 offset:32640
	s_waitcnt lgkmcnt(0)
	v_mfma_f32_16x16x32_bf16 v[152:155], v[122:125], v[4:7], v[118:121]
	s_nop 3
	v_lshlrev_b32_e32 v118, 3, v126
	v_sub_u32_e32 v142, v132, v118
	v_mfma_f32_16x16x32_bf16 v[108:111], v[122:125], v[20:23], v[108:111]
	v_add_u32_e32 v125, 0xffffffb0, v142
	v_cmp_lt_i32_e32 vcc, -1, v125
	s_nop 1
	v_cndmask_b32_e32 v118, v207, v114, vcc
	v_cmp_lt_i32_e32 vcc, 0, v125
	s_nop 1
	v_cndmask_b32_e32 v120, v207, v115, vcc
	v_cmp_lt_i32_e32 vcc, 1, v125
	v_max_f32_e32 v143, v120, v120
	s_nop 0
	v_cndmask_b32_e32 v122, v207, v116, vcc
	v_cmp_lt_i32_e32 vcc, 2, v125
	s_nop 1
	v_cndmask_b32_e32 v124, v207, v117, vcc
	v_cmp_lt_i32_e32 vcc, 3, v125
	s_nop 1
	v_cndmask_b32_e32 v126, v207, v144, vcc
	v_cmp_lt_i32_e32 vcc, 4, v125
	v_max_f32_e32 v144, v118, v118
	v_max_f32_e32 v143, v144, v143
	v_cndmask_b32_e32 v127, v207, v145, vcc
	v_cmp_lt_i32_e32 vcc, 5, v125
	v_max3_f32 v143, v143, v122, v124
	v_max3_f32 v143, v143, v126, v127
	v_cndmask_b32_e32 v140, v207, v146, vcc
	v_cmp_lt_i32_e32 vcc, 6, v125
	s_nop 1
	v_cndmask_b32_e32 v141, v207, v147, vcc
	v_cmp_lt_i32_e32 vcc, 31, v125
	v_max3_f32 v143, v143, v140, v141
	s_nop 0
	v_cndmask_b32_e32 v114, v207, v148, vcc
	v_cmp_lt_i32_e32 vcc, 32, v125
	s_nop 1
	v_cndmask_b32_e32 v115, v207, v149, vcc
	v_cmp_lt_i32_e32 vcc, 33, v125
	v_max3_f32 v143, v143, v114, v115
	s_nop 0
	v_cndmask_b32_e32 v116, v207, v150, vcc
	v_cmp_lt_i32_e32 vcc, 34, v125
	s_nop 1
	v_cndmask_b32_e32 v117, v207, v151, vcc
	v_cmp_lt_i32_e32 vcc, 35, v125
	v_max3_f32 v143, v143, v116, v117
	s_nop 0
	v_cndmask_b32_e32 v119, v207, v152, vcc
	v_cmp_lt_i32_e32 vcc, 36, v125
	s_nop 1
	v_cndmask_b32_e32 v121, v207, v153, vcc
	v_cmp_lt_i32_e32 vcc, 37, v125
	v_max3_f32 v143, v143, v119, v121
	s_nop 0
	v_cndmask_b32_e32 v123, v207, v154, vcc
	v_cmp_lt_i32_e32 vcc, 38, v125
	s_nop 1
	v_cndmask_b32_e32 v125, v207, v155, vcc
	v_max3_f32 v143, v143, v123, v125
	v_sub_f32_e32 v144, v143, v136
	v_mul_f32_e32 v144, 1.0, v144
	v_cmp_lt_f32_e32 vcc, s42, v144
	s_cbranch_vccz .LBB0_1971
	v_mov_b32_e32 v144, v143
	s_nop 1
	v_permlane16_swap_b32_e32 v143, v144
	v_max_f32_e32 v143, v144, v143
	v_mov_b32_e32 v144, v143
	s_nop 1
	v_permlane32_swap_b32_e32 v143, v144
	v_max3_f32 v144, v136, v143, v144
	v_sub_f32_e32 v136, v136, v144
	v_mul_f32_e32 v136, 1.0, v136
	v_exp_f32_e32 v136, v136
	v_mov_b32_e32 v145, v137
	v_mul_f32_e32 v134, v134, v136
	v_pk_mul_f32 v[50:51], v[50:51], v[136:137] op_sel_hi:[1,0]
	v_pk_mul_f32 v[48:49], v[48:49], v[136:137] op_sel_hi:[1,0]
	v_pk_mul_f32 v[78:79], v[78:79], v[136:137] op_sel_hi:[1,0]
	v_pk_mul_f32 v[76:77], v[76:77], v[136:137] op_sel_hi:[1,0]
	v_pk_mul_f32 v[86:87], v[86:87], v[136:137] op_sel_hi:[1,0]
	v_pk_mul_f32 v[84:85], v[84:85], v[136:137] op_sel_hi:[1,0]
	v_pk_mul_f32 v[94:95], v[94:95], v[136:137] op_sel_hi:[1,0]
	v_pk_mul_f32 v[92:93], v[92:93], v[136:137] op_sel_hi:[1,0]
	v_mul_f32_e32 v136, -1.0, v144
	v_fmamk_f32 v118, v118, 0x3f800000, v136
	v_exp_f32_e32 v118, v118
	v_fmamk_f32 v120, v120, 0x3f800000, v136
	v_exp_f32_e32 v120, v120
	v_fmamk_f32 v122, v122, 0x3f800000, v136
	v_exp_f32_e32 v122, v122
	v_fmamk_f32 v124, v124, 0x3f800000, v136
	v_exp_f32_e32 v124, v124
	v_fmamk_f32 v126, v126, 0x3f800000, v136
	v_add_f32_e32 v137, 0, v118
	v_exp_f32_e32 v126, v126
	v_fmamk_f32 v127, v127, 0x3f800000, v136
	v_add_f32_e32 v137, v120, v137
	v_exp_f32_e32 v127, v127
	v_fmamk_f32 v140, v140, 0x3f800000, v136
	v_add_f32_e32 v137, v122, v137
	v_exp_f32_e32 v140, v140
	v_fmamk_f32 v141, v141, 0x3f800000, v136
	v_add_f32_e32 v137, v124, v137
	v_exp_f32_e32 v141, v141
	v_fmamk_f32 v114, v114, 0x3f800000, v136
	v_add_f32_e32 v137, v126, v137
	v_exp_f32_e32 v114, v114
	v_fmamk_f32 v115, v115, 0x3f800000, v136
	v_add_f32_e32 v137, v127, v137
	v_exp_f32_e32 v115, v115
	v_fmamk_f32 v116, v116, 0x3f800000, v136
	v_add_f32_e32 v137, v140, v137
	v_exp_f32_e32 v116, v116
	v_fmamk_f32 v117, v117, 0x3f800000, v136
	v_add_f32_e32 v137, v141, v137
	v_exp_f32_e32 v117, v117
	v_fmamk_f32 v119, v119, 0x3f800000, v136
	v_add_f32_e32 v137, v114, v137
	v_exp_f32_e32 v119, v119
	v_fmamk_f32 v121, v121, 0x3f800000, v136
	v_add_f32_e32 v137, v115, v137
	v_exp_f32_e32 v121, v121
	v_fmamk_f32 v123, v123, 0x3f800000, v136
	v_add_f32_e32 v137, v116, v137
	v_exp_f32_e32 v123, v123
	v_fmac_f32_e32 v136, 1.0, v125
	v_add_f32_e32 v137, v117, v137
	v_exp_f32_e32 v125, v136
	v_add_f32_e32 v136, v119, v137
	v_add_f32_e32 v136, v121, v136
	v_add_f32_e32 v136, v123, v136
	v_add_f32_e32 v143, v125, v136
	v_mov_b64_e32 v[136:137], v[144:145]
	s_branch .LBB0_1972

.LBB0_1972:
	v_subrev_u32_e32 v150, 64, v142
	v_cmp_lt_i32_e32 vcc, -1, v150
	v_add_f32_e32 v134, v134, v143
	s_nop 0
	v_cndmask_b32_e32 v149, v207, v96, vcc
	v_cmp_lt_i32_e32 vcc, 0, v150
	s_nop 1
	v_cndmask_b32_e32 v148, v207, v97, vcc
	v_cmp_lt_i32_e32 vcc, 1, v150
	s_nop 1
	v_cndmask_b32_e32 v147, v207, v98, vcc
	v_cmp_lt_i32_e32 vcc, 2, v150
	s_nop 1
	v_cndmask_b32_e32 v146, v207, v99, vcc
	v_cmp_lt_i32_e32 vcc, 3, v150
	s_nop 1
	v_cndmask_b32_e32 v145, v207, v100, vcc
	v_cmp_lt_i32_e32 vcc, 4, v150
	s_nop 1
	v_cndmask_b32_e32 v144, v207, v101, vcc
	v_cmp_lt_i32_e32 vcc, 5, v150
	v_max_f32_e32 v101, v148, v148
	s_nop 0
	v_cndmask_b32_e32 v143, v207, v102, vcc
	v_cmp_lt_i32_e32 vcc, 6, v150
	s_nop 1
	v_cndmask_b32_e32 v142, v207, v103, vcc
	v_cmp_lt_i32_e32 vcc, 31, v150
	v_max_f32_e32 v103, v149, v149
	v_max_f32_e32 v101, v103, v101
	v_cndmask_b32_e32 v97, v207, v104, vcc
	v_cmp_lt_i32_e32 vcc, 32, v150
	v_max3_f32 v101, v101, v147, v146
	v_max3_f32 v101, v101, v145, v144
	v_cndmask_b32_e32 v98, v207, v105, vcc
	v_cmp_lt_i32_e32 vcc, 33, v150
	v_max3_f32 v101, v101, v143, v142
	v_max3_f32 v101, v101, v97, v98
	v_cndmask_b32_e32 v99, v207, v106, vcc
	v_cmp_lt_i32_e32 vcc, 34, v150
	s_nop 1
	v_cndmask_b32_e32 v100, v207, v107, vcc
	v_cmp_lt_i32_e32 vcc, 35, v150
	v_max3_f32 v101, v101, v99, v100
	s_nop 0
	v_cndmask_b32_e32 v102, v207, v108, vcc
	v_cmp_lt_i32_e32 vcc, 36, v150
	s_nop 1
	v_cndmask_b32_e32 v104, v207, v109, vcc
	v_cmp_lt_i32_e32 vcc, 37, v150
	v_max3_f32 v101, v101, v102, v104
	s_nop 0
	v_cndmask_b32_e32 v106, v207, v110, vcc
	v_cmp_lt_i32_e32 vcc, 38, v150
	s_nop 1
	v_cndmask_b32_e32 v96, v207, v111, vcc
	v_max3_f32 v101, v101, v106, v96
	v_sub_f32_e32 v103, v101, v137
	v_mul_f32_e32 v103, 1.0, v103
	v_cmp_lt_f32_e32 vcc, s42, v103
	s_cbranch_vccnz .LBB0_1935
	v_mul_f32_e32 v108, -1.0, v137
	v_fmamk_f32 v101, v149, 0x3f800000, v108
	v_exp_f32_e32 v101, v101
	v_fmamk_f32 v103, v148, 0x3f800000, v108
	v_exp_f32_e32 v103, v103
	v_fmamk_f32 v105, v147, 0x3f800000, v108
	v_exp_f32_e32 v105, v105
	v_fmamk_f32 v107, v146, 0x3f800000, v108
	v_exp_f32_e32 v107, v107
	v_fmamk_f32 v109, v145, 0x3f800000, v108
	v_exp_f32_e32 v109, v109
	v_fmamk_f32 v110, v144, 0x3f800000, v108
	v_fmamk_f32 v111, v143, 0x3f800000, v108
	v_fmamk_f32 v142, v142, 0x3f800000, v108
	v_fmamk_f32 v97, v97, 0x3f800000, v108
	v_fmamk_f32 v98, v98, 0x3f800000, v108
	v_fmamk_f32 v99, v99, 0x3f800000, v108
	v_fmamk_f32 v100, v100, 0x3f800000, v108
	v_fmamk_f32 v102, v102, 0x3f800000, v108
	v_fmamk_f32 v104, v104, 0x3f800000, v108
	v_fmamk_f32 v106, v106, 0x3f800000, v108
	v_fmac_f32_e32 v108, 1.0, v96
	v_add_f32_e32 v96, 0, v101
	v_exp_f32_e32 v110, v110
	v_add_f32_e32 v96, v103, v96
	v_exp_f32_e32 v111, v111
	v_add_f32_e32 v96, v105, v96
	v_exp_f32_e32 v142, v142
	v_add_f32_e32 v96, v107, v96
	v_exp_f32_e32 v97, v97
	v_add_f32_e32 v96, v109, v96
	v_exp_f32_e32 v98, v98
	v_add_f32_e32 v96, v110, v96
	v_exp_f32_e32 v99, v99
	v_add_f32_e32 v96, v111, v96
	v_exp_f32_e32 v100, v100
	v_add_f32_e32 v96, v142, v96
	v_exp_f32_e32 v102, v102
	v_add_f32_e32 v96, v97, v96
	v_add_f32_e32 v96, v98, v96
	v_add_f32_e32 v96, v99, v96
	v_add_f32_e32 v96, v100, v96
	v_exp_f32_e32 v104, v104
	v_exp_f32_e32 v106, v106
	v_exp_f32_e32 v108, v108
	v_add_f32_e32 v96, v102, v96
	s_branch .LBB0_1936
